# phase D gated-merge epilogue rewritten: gate slab loads kept in flight in a 4-slot ring with counted waits, branch-specialised scaling (same math)
# speedup vs baseline: 1.0154x; 1.0154x over previous
; __device__ __forceinline__ int lane_fresh() { int l; asm volatile("v_mbcnt_lo_u32_b32 %0, -1, 0\n\tv_mbcnt_hi_u32_b32 %0, -1, %0" : "=v"(l)); return l; }
; __device__ __forceinline__ void phaseD(const Params& p, const int wv, const int rep) {
;     ...
;       const int gnum = (br == 0) ? 0 : (br == 2) ? 1024 : 2048, gden = (br == 0) ? 1024 : 2048;
;       const int lane_e = lane_fresh(), fr = lane_e & 15, fq = lane_e >> 4;
;       const int r0 = brow + wr * 64 + fr, c0 = bcol + wc * 32 + fq * 4;
;       u32x4 gw[4][2], dw[4][2];
;       const int poff = (fq & 1) * 16 + (fq >> 1) * 8;
;     ...
;       D_LOAD(0, 0); D_LOAD(1, 1); D_LOAD(2, 2); D_LOAD(3, 3);
;       if (br < 3) { const u16 *An, *Bn; int ldn; opnd(br + 1, An, Bn, ldn); kloop_t<1, false>(An, ldn, Bn, ldn, 512, acc, wv); }
; #pragma unroll
;       for (int g = 0; g < 8; ++g) {
;         __builtin_amdgcn_sched_barrier(0);
;         const int ai = g >> 2, m = g & 3, rrow = ai * 128 + wr * 64 + m * 16 + fr, row_ = brow + rrow;
;         const float rs0 = rs_l[rrow * 2], rs1 = rs_l[rrow * 2 + 1];
;         const float rsc = (br == 0) ? __builtin_amdgcn_rcpf(rs0) : (br == 1) ? rs0 * __builtin_amdgcn_rcpf(rs1) : (br == 2) ? rs1 : 1.f;
.LBB0_707:
	v_mbcnt_lo_u32_b32 v0, -1, 0
	v_mbcnt_hi_u32_b32 v0, -1, v0
	v_and_b32_e32 v136, 15, v0
	v_and_b32_e32 v130, 16, v0
	v_ashrrev_i32_e32 v131, 2, v0
	v_and_b32_e32 v131, -8, v131
	v_add_u32_e32 v137, v131, v130
	v_or_b32_e32 v141, s87, v136
	v_lshl_add_u32 v133, v141, 3, 16
	v_add_u32_e32 v133, 0x20000, v133
	s_cmp_eq_u32 s33, 1
	s_cbranch_scc1 .Ldm_br1
	v_or_b32_e32 v130, s91, v136
	v_mul_lo_u32 v132, v130, s88
	v_lshl_add_u32 v132, v137, 1, v132
	s_cmp_eq_u32 s33, 3
	s_cbranch_scc1 .Ldm_br3
	s_cmp_eq_u32 s33, 2
	s_cselect_b64 s[0:1], -1, 0
	s_cselect_b32 s4, 0x800, 0
	s_add_u32 s56, s52, s4
	s_addc_u32 s57, s53, 0
	s_add_u32 s62, s56, 0x800
	s_addc_u32 s63, s57, 0
	global_load_dwordx4 v[192:195], v132, s[56:57]
	global_load_dwordx4 v[196:199], v132, s[56:57] offset:256
	global_load_dwordx4 v[200:203], v132, s[62:63]
	global_load_dwordx4 v[204:207], v132, s[62:63] offset:256
	v_add_u32_e32 v138, 0x18000, v132
	global_load_dwordx4 v[208:211], v138, s[56:57]
	global_load_dwordx4 v[212:215], v138, s[56:57] offset:256
	global_load_dwordx4 v[216:219], v138, s[62:63]
	global_load_dwordx4 v[220:223], v138, s[62:63] offset:256
	v_add_u32_e32 v138, 0x30000, v132
	global_load_dwordx4 v[224:227], v138, s[56:57]
	global_load_dwordx4 v[228:231], v138, s[56:57] offset:256
	global_load_dwordx4 v[232:235], v138, s[62:63]
	global_load_dwordx4 v[236:239], v138, s[62:63] offset:256
	v_add_u32_e32 v138, 0x48000, v132
	global_load_dwordx4 v[240:243], v138, s[56:57]
	global_load_dwordx4 v[244:247], v138, s[56:57] offset:256
	global_load_dwordx4 v[176:179], v138, s[62:63]
	global_load_dwordx4 v[180:183], v138, s[62:63] offset:256
	ds_read_b64 v[160:161], v133
	ds_read_b64 v[162:163], v133 offset:128
	ds_read_b64 v[164:165], v133 offset:256
	ds_read_b64 v[166:167], v133 offset:384
	ds_read_b64 v[168:169], v133 offset:1024
	ds_read_b64 v[170:171], v133 offset:1152
	ds_read_b64 v[172:173], v133 offset:1280
	ds_read_b64 v[174:175], v133 offset:1408

; __device__ __forceinline__ u32x2 pack4(f32x4 v) { u32x2 r; r.x = cvt_pk(v[0], v[1]); r.y = cvt_pk(v[2], v[3]); return r; }
; __device__ __forceinline__ f32x4 unpack4(u32x2 w) { return (f32x4){bflo(w.x), bfhi(w.x), bflo(w.y), bfhi(w.y)}; }
; __device__ __forceinline__ void phaseD(const Params& p, const int wv, const int rep) {
;     ...
; #pragma unroll
;       for (int g = 0; g < 8; ++g) {
;         __builtin_amdgcn_sched_barrier(0);
;         const int ai = g >> 2, m = g & 3, rrow = ai * 128 + wr * 64 + m * 16 + fr, row_ = brow + rrow;
;         const float rs0 = rs_l[rrow * 2], rs1 = rs_l[rrow * 2 + 1];
;         const float rsc = (br == 0) ? __builtin_amdgcn_rcpf(rs0) : (br == 1) ? rs0 * __builtin_amdgcn_rcpf(rs1) : (br == 2) ? rs1 : 1.f;
; #pragma unroll
;         for (int bj = 0; bj < 2; ++bj) {
;           u32x2 gnp[2], gdp[2];
;           unpair16(gw[g & 3][bj], gnp[0], gnp[1]); unpair16(dw[g & 3][bj], gdp[0], gdp[1]);
; #pragma unroll
;           for (int n = 0; n < 2; ++n) {
;             const f32x4 gn = unpack4(gnp[n]), gd = unpack4(gdp[n]);
;             f32x4 sc;
; #pragma unroll
;             for (int e = 0; e < 4; ++e) sc[e] = gn[e] * rsc * __builtin_amdgcn_rcpf(fmaxf(gd[e], 1e-30f));
;             acc[ai][bj][m][n] = acc[ai][bj][m][n] * sc;
;           }
;         }
;         if (br == 3) {
;           u16* mrow = MERGED + (size_t)row_ * 1024 + bcol + wc * 32;
;           store_pair16(mrow, pack4(acc[ai][0][m][0]), pack4(acc[ai][0][m][1]), fq);
;           store_pair16(mrow + 128, pack4(acc[ai][1][m][0]), pack4(acc[ai][1][m][1]), fq);
;         }
;         __builtin_amdgcn_sched_barrier(0);
;         if (g < 4) D_LOAD(g + 4, g & 3);
.LBB0_775:
	s_waitcnt lgkmcnt(0)
	v_rcp_f32_e32 v160, v160
	v_rcp_f32_e32 v162, v162
	v_rcp_f32_e32 v164, v164
	v_rcp_f32_e32 v166, v166
	v_rcp_f32_e32 v168, v168
	v_rcp_f32_e32 v170, v170
	v_rcp_f32_e32 v172, v172
	v_rcp_f32_e32 v174, v174
	s_nop 0
	v_cndmask_b32_e64 v160, v160, v161, s[0:1]
	v_cndmask_b32_e64 v162, v162, v163, s[0:1]
	v_cndmask_b32_e64 v164, v164, v165, s[0:1]
	v_cndmask_b32_e64 v166, v166, v167, s[0:1]
	v_cndmask_b32_e64 v168, v168, v169, s[0:1]
	v_cndmask_b32_e64 v170, v170, v171, s[0:1]
	v_cndmask_b32_e64 v172, v172, v173, s[0:1]
	v_cndmask_b32_e64 v174, v174, v175, s[0:1]
	s_waitcnt vmcnt(20)
	v_permlane16_swap_b32_e32 v200, v202
	v_permlane16_swap_b32_e32 v201, v203
	v_permlane16_swap_b32_e32 v192, v194
	v_permlane16_swap_b32_e32 v193, v195
	v_lshlrev_b32_e32 v152, 16, v200
	v_and_b32_e32 v153, 0xffff0000, v200
	v_lshlrev_b32_e32 v154, 16, v201
	v_and_b32_e32 v155, 0xffff0000, v201
	v_lshlrev_b32_e32 v156, 16, v202
	v_and_b32_e32 v157, 0xffff0000, v202
	v_lshlrev_b32_e32 v158, 16, v203
	v_and_b32_e32 v159, 0xffff0000, v203
	v_max_f32_e32 v152, 0xda24260, v152
	v_max_f32_e32 v153, 0xda24260, v153
	v_max_f32_e32 v154, 0xda24260, v154
	v_max_f32_e32 v155, 0xda24260, v155
	v_max_f32_e32 v156, 0xda24260, v156
	v_max_f32_e32 v157, 0xda24260, v157
	v_max_f32_e32 v158, 0xda24260, v158
	v_max_f32_e32 v159, 0xda24260, v159
	v_rcp_f32_e32 v152, v152
	v_rcp_f32_e32 v153, v153
	v_rcp_f32_e32 v154, v154
	v_rcp_f32_e32 v155, v155
	v_rcp_f32_e32 v156, v156
	v_rcp_f32_e32 v157, v157
	v_rcp_f32_e32 v158, v158
	v_rcp_f32_e32 v159, v159
	v_lshlrev_b32_e32 v144, 16, v192
	v_and_b32_e32 v145, 0xffff0000, v192
	v_lshlrev_b32_e32 v146, 16, v193
	v_and_b32_e32 v147, 0xffff0000, v193
	v_lshlrev_b32_e32 v148, 16, v194
	v_and_b32_e32 v149, 0xffff0000, v194
	v_lshlrev_b32_e32 v150, 16, v195
	v_and_b32_e32 v151, 0xffff0000, v195
	v_pk_mul_f32 v[144:145], v[160:161], v[144:145] op_sel_hi:[0,1]
	v_pk_mul_f32 v[146:147], v[160:161], v[146:147] op_sel_hi:[0,1]
	v_pk_mul_f32 v[148:149], v[160:161], v[148:149] op_sel_hi:[0,1]
	v_pk_mul_f32 v[150:151], v[160:161], v[150:151] op_sel_hi:[0,1]
	v_pk_mul_f32 v[144:145], v[144:145], v[152:153]
	v_pk_mul_f32 v[146:147], v[146:147], v[154:155]
	v_pk_mul_f32 v[148:149], v[148:149], v[156:157]
	v_pk_mul_f32 v[150:151], v[150:151], v[158:159]
	v_pk_mul_f32 v[30:31], v[30:31], v[144:145]
	v_pk_mul_f32 v[32:33], v[32:33], v[146:147]
	v_pk_mul_f32 v[38:39], v[38:39], v[148:149]
	v_pk_mul_f32 v[40:41], v[40:41], v[150:151]
	v_permlane16_swap_b32_e32 v204, v206
	v_permlane16_swap_b32_e32 v205, v207
	v_permlane16_swap_b32_e32 v196, v198
	v_permlane16_swap_b32_e32 v197, v199
	v_lshlrev_b32_e32 v152, 16, v204
	v_and_b32_e32 v153, 0xffff0000, v204
	v_lshlrev_b32_e32 v154, 16, v205
	v_and_b32_e32 v155, 0xffff0000, v205
	v_lshlrev_b32_e32 v156, 16, v206
	v_and_b32_e32 v157, 0xffff0000, v206
	v_lshlrev_b32_e32 v158, 16, v207
	v_and_b32_e32 v159, 0xffff0000, v207
	v_max_f32_e32 v152, 0xda24260, v152
	v_max_f32_e32 v153, 0xda24260, v153
	v_max_f32_e32 v154, 0xda24260, v154
	v_max_f32_e32 v155, 0xda24260, v155
	v_max_f32_e32 v156, 0xda24260, v156
	v_max_f32_e32 v157, 0xda24260, v157
	v_max_f32_e32 v158, 0xda24260, v158
	v_max_f32_e32 v159, 0xda24260, v159
	v_rcp_f32_e32 v152, v152
	v_rcp_f32_e32 v153, v153
	v_rcp_f32_e32 v154, v154
	v_rcp_f32_e32 v155, v155
	v_rcp_f32_e32 v156, v156
	v_rcp_f32_e32 v157, v157
	v_rcp_f32_e32 v158, v158
	v_rcp_f32_e32 v159, v159
	v_lshlrev_b32_e32 v144, 16, v196
	v_and_b32_e32 v145, 0xffff0000, v196
	v_lshlrev_b32_e32 v146, 16, v197
	v_and_b32_e32 v147, 0xffff0000, v197
	v_lshlrev_b32_e32 v148, 16, v198
	v_and_b32_e32 v149, 0xffff0000, v198
	v_lshlrev_b32_e32 v150, 16, v199
	v_and_b32_e32 v151, 0xffff0000, v199
	v_pk_mul_f32 v[144:145], v[160:161], v[144:145] op_sel_hi:[0,1]
	v_pk_mul_f32 v[146:147], v[160:161], v[146:147] op_sel_hi:[0,1]
	v_pk_mul_f32 v[148:149], v[160:161], v[148:149] op_sel_hi:[0,1]
	v_pk_mul_f32 v[150:151], v[160:161], v[150:151] op_sel_hi:[0,1]
	v_pk_mul_f32 v[144:145], v[144:145], v[152:153]
	v_pk_mul_f32 v[146:147], v[146:147], v[154:155]
	v_pk_mul_f32 v[148:149], v[148:149], v[156:157]
	v_pk_mul_f32 v[150:151], v[150:151], v[158:159]
	v_pk_mul_f32 v[42:43], v[42:43], v[144:145]
	v_pk_mul_f32 v[44:45], v[44:45], v[146:147]
	v_pk_mul_f32 v[46:47], v[46:47], v[148:149]
	v_pk_mul_f32 v[48:49], v[48:49], v[150:151]
	v_add_u32_e32 v138, 0xc0000, v132
	global_load_dwordx4 v[192:195], v138, s[56:57]
	global_load_dwordx4 v[196:199], v138, s[56:57] offset:256
	global_load_dwordx4 v[200:203], v138, s[62:63]
	global_load_dwordx4 v[204:207], v138, s[62:63] offset:256
	s_waitcnt vmcnt(20)
; __device__ __forceinline__ f32x4 unpack4(u32x2 w) { return (f32x4){bflo(w.x), bfhi(w.x), bflo(w.y), bfhi(w.y)}; }
; __device__ __forceinline__ void phaseD(const Params& p, const int wv, const int rep) {
;     ...
;       for (int g = 0; g < 8; ++g) {
;         __builtin_amdgcn_sched_barrier(0);
;         const int ai = g >> 2, m = g & 3, rrow = ai * 128 + wr * 64 + m * 16 + fr, row_ = brow + rrow;
;         const float rs0 = rs_l[rrow * 2], rs1 = rs_l[rrow * 2 + 1];
;         const float rsc = (br == 0) ? __builtin_amdgcn_rcpf(rs0) : (br == 1) ? rs0 * __builtin_amdgcn_rcpf(rs1) : (br == 2) ? rs1 : 1.f;
; #pragma unroll
;         for (int bj = 0; bj < 2; ++bj) {
;           u32x2 gnp[2], gdp[2];
;           unpair16(gw[g & 3][bj], gnp[0], gnp[1]); unpair16(dw[g & 3][bj], gdp[0], gdp[1]);
; #pragma unroll
;           for (int n = 0; n < 2; ++n) {
;             const f32x4 gn = unpack4(gnp[n]), gd = unpack4(gdp[n]);
;             f32x4 sc;
; #pragma unroll
;             for (int e = 0; e < 4; ++e) sc[e] = gn[e] * rsc * __builtin_amdgcn_rcpf(fmaxf(gd[e], 1e-30f));
;             acc[ai][bj][m][n] = acc[ai][bj][m][n] * sc;
;           }
;         }
	v_permlane16_swap_b32_e32 v216, v218
	v_permlane16_swap_b32_e32 v217, v219
	v_permlane16_swap_b32_e32 v208, v210
	v_permlane16_swap_b32_e32 v209, v211
	v_lshlrev_b32_e32 v152, 16, v216
	v_and_b32_e32 v153, 0xffff0000, v216
	v_lshlrev_b32_e32 v154, 16, v217
	v_and_b32_e32 v155, 0xffff0000, v217
	v_lshlrev_b32_e32 v156, 16, v218
	v_and_b32_e32 v157, 0xffff0000, v218
	v_lshlrev_b32_e32 v158, 16, v219
	v_and_b32_e32 v159, 0xffff0000, v219
	v_max_f32_e32 v152, 0xda24260, v152
	v_max_f32_e32 v153, 0xda24260, v153
	v_max_f32_e32 v154, 0xda24260, v154
	v_max_f32_e32 v155, 0xda24260, v155
	v_max_f32_e32 v156, 0xda24260, v156
	v_max_f32_e32 v157, 0xda24260, v157
	v_max_f32_e32 v158, 0xda24260, v158
	v_max_f32_e32 v159, 0xda24260, v159
	v_rcp_f32_e32 v152, v152
	v_rcp_f32_e32 v153, v153
	v_rcp_f32_e32 v154, v154
	v_rcp_f32_e32 v155, v155
	v_rcp_f32_e32 v156, v156
	v_rcp_f32_e32 v157, v157
	v_rcp_f32_e32 v158, v158
	v_rcp_f32_e32 v159, v159
	v_lshlrev_b32_e32 v144, 16, v208
	v_and_b32_e32 v145, 0xffff0000, v208
	v_lshlrev_b32_e32 v146, 16, v209
	v_and_b32_e32 v147, 0xffff0000, v209
	v_lshlrev_b32_e32 v148, 16, v210
	v_and_b32_e32 v149, 0xffff0000, v210
	v_lshlrev_b32_e32 v150, 16, v211
	v_and_b32_e32 v151, 0xffff0000, v211
	v_pk_mul_f32 v[144:145], v[162:163], v[144:145] op_sel_hi:[0,1]
	v_pk_mul_f32 v[146:147], v[162:163], v[146:147] op_sel_hi:[0,1]
	v_pk_mul_f32 v[148:149], v[162:163], v[148:149] op_sel_hi:[0,1]
	v_pk_mul_f32 v[150:151], v[162:163], v[150:151] op_sel_hi:[0,1]
	v_pk_mul_f32 v[144:145], v[144:145], v[152:153]
	v_pk_mul_f32 v[146:147], v[146:147], v[154:155]
	v_pk_mul_f32 v[148:149], v[148:149], v[156:157]
	v_pk_mul_f32 v[150:151], v[150:151], v[158:159]
	v_pk_mul_f32 v[70:71], v[70:71], v[144:145]
	v_pk_mul_f32 v[72:73], v[72:73], v[146:147]
	v_pk_mul_f32 v[78:79], v[78:79], v[148:149]
	v_pk_mul_f32 v[80:81], v[80:81], v[150:151]
	v_permlane16_swap_b32_e32 v220, v222
	v_permlane16_swap_b32_e32 v221, v223
	v_permlane16_swap_b32_e32 v212, v214
	v_permlane16_swap_b32_e32 v213, v215
	v_lshlrev_b32_e32 v152, 16, v220
	v_and_b32_e32 v153, 0xffff0000, v220
	v_lshlrev_b32_e32 v154, 16, v221
	v_and_b32_e32 v155, 0xffff0000, v221
	v_lshlrev_b32_e32 v156, 16, v222
	v_and_b32_e32 v157, 0xffff0000, v222
	v_lshlrev_b32_e32 v158, 16, v223
	v_and_b32_e32 v159, 0xffff0000, v223
	v_max_f32_e32 v152, 0xda24260, v152
	v_max_f32_e32 v153, 0xda24260, v153
	v_max_f32_e32 v154, 0xda24260, v154
	v_max_f32_e32 v155, 0xda24260, v155
	v_max_f32_e32 v156, 0xda24260, v156
	v_max_f32_e32 v157, 0xda24260, v157
	v_max_f32_e32 v158, 0xda24260, v158
	v_max_f32_e32 v159, 0xda24260, v159
	v_rcp_f32_e32 v152, v152
	v_rcp_f32_e32 v153, v153
	v_rcp_f32_e32 v154, v154
	v_rcp_f32_e32 v155, v155
	v_rcp_f32_e32 v156, v156
	v_rcp_f32_e32 v157, v157
	v_rcp_f32_e32 v158, v158
	v_rcp_f32_e32 v159, v159
	v_lshlrev_b32_e32 v144, 16, v212
	v_and_b32_e32 v145, 0xffff0000, v212
	v_lshlrev_b32_e32 v146, 16, v213
	v_and_b32_e32 v147, 0xffff0000, v213
	v_lshlrev_b32_e32 v148, 16, v214
	v_and_b32_e32 v149, 0xffff0000, v214
	v_lshlrev_b32_e32 v150, 16, v215
	v_and_b32_e32 v151, 0xffff0000, v215
	v_pk_mul_f32 v[144:145], v[162:163], v[144:145] op_sel_hi:[0,1]
	v_pk_mul_f32 v[146:147], v[162:163], v[146:147] op_sel_hi:[0,1]
	v_pk_mul_f32 v[148:149], v[162:163], v[148:149] op_sel_hi:[0,1]
	v_pk_mul_f32 v[150:151], v[162:163], v[150:151] op_sel_hi:[0,1]
	v_pk_mul_f32 v[144:145], v[144:145], v[152:153]
	v_pk_mul_f32 v[146:147], v[146:147], v[154:155]
	v_pk_mul_f32 v[148:149], v[148:149], v[156:157]
	v_pk_mul_f32 v[150:151], v[150:151], v[158:159]
	v_pk_mul_f32 v[82:83], v[82:83], v[144:145]
	v_pk_mul_f32 v[84:85], v[84:85], v[146:147]
	v_pk_mul_f32 v[90:91], v[90:91], v[148:149]
	v_pk_mul_f32 v[92:93], v[92:93], v[150:151]
	v_add_u32_e32 v138, 0xd8000, v132
	global_load_dwordx4 v[208:211], v138, s[56:57]
	global_load_dwordx4 v[212:215], v138, s[56:57] offset:256
	global_load_dwordx4 v[216:219], v138, s[62:63]
	global_load_dwordx4 v[220:223], v138, s[62:63] offset:256
	s_waitcnt vmcnt(20)
	v_permlane16_swap_b32_e32 v232, v234
	v_permlane16_swap_b32_e32 v233, v235
	v_permlane16_swap_b32_e32 v224, v226
	v_permlane16_swap_b32_e32 v225, v227
	v_lshlrev_b32_e32 v152, 16, v232
	v_and_b32_e32 v153, 0xffff0000, v232
	v_lshlrev_b32_e32 v154, 16, v233
	v_and_b32_e32 v155, 0xffff0000, v233
	v_lshlrev_b32_e32 v156, 16, v234
	v_and_b32_e32 v157, 0xffff0000, v234
	v_lshlrev_b32_e32 v158, 16, v235
	v_and_b32_e32 v159, 0xffff0000, v235
	v_max_f32_e32 v152, 0xda24260, v152
	v_max_f32_e32 v153, 0xda24260, v153
	v_max_f32_e32 v154, 0xda24260, v154
	v_max_f32_e32 v155, 0xda24260, v155
	v_max_f32_e32 v156, 0xda24260, v156
	v_max_f32_e32 v157, 0xda24260, v157
	v_max_f32_e32 v158, 0xda24260, v158
	v_max_f32_e32 v159, 0xda24260, v159
	v_rcp_f32_e32 v152, v152
	v_rcp_f32_e32 v153, v153
	v_rcp_f32_e32 v154, v154
	v_rcp_f32_e32 v155, v155
	v_rcp_f32_e32 v156, v156
	v_rcp_f32_e32 v157, v157
	v_rcp_f32_e32 v158, v158
	v_rcp_f32_e32 v159, v159
	v_lshlrev_b32_e32 v144, 16, v224
	v_and_b32_e32 v145, 0xffff0000, v224
	v_lshlrev_b32_e32 v146, 16, v225
	v_and_b32_e32 v147, 0xffff0000, v225
	v_lshlrev_b32_e32 v148, 16, v226
	v_and_b32_e32 v149, 0xffff0000, v226
	v_lshlrev_b32_e32 v150, 16, v227
	v_and_b32_e32 v151, 0xffff0000, v227
	v_pk_mul_f32 v[144:145], v[164:165], v[144:145] op_sel_hi:[0,1]
	v_pk_mul_f32 v[146:147], v[164:165], v[146:147] op_sel_hi:[0,1]
	v_pk_mul_f32 v[148:149], v[164:165], v[148:149] op_sel_hi:[0,1]
	v_pk_mul_f32 v[150:151], v[164:165], v[150:151] op_sel_hi:[0,1]
	v_pk_mul_f32 v[144:145], v[144:145], v[152:153]
	v_pk_mul_f32 v[146:147], v[146:147], v[154:155]
	v_pk_mul_f32 v[148:149], v[148:149], v[156:157]
; __device__ __forceinline__ u32x2 pack4(f32x4 v) { u32x2 r; r.x = cvt_pk(v[0], v[1]); r.y = cvt_pk(v[2], v[3]); return r; }
; __device__ __forceinline__ f32x4 unpack4(u32x2 w) { return (f32x4){bflo(w.x), bfhi(w.x), bflo(w.y), bfhi(w.y)}; }
; __device__ __forceinline__ void phaseD(const Params& p, const int wv, const int rep) {
;     ...
;       for (int g = 0; g < 8; ++g) {
;         __builtin_amdgcn_sched_barrier(0);
;         const int ai = g >> 2, m = g & 3, rrow = ai * 128 + wr * 64 + m * 16 + fr, row_ = brow + rrow;
;         const float rs0 = rs_l[rrow * 2], rs1 = rs_l[rrow * 2 + 1];
;         const float rsc = (br == 0) ? __builtin_amdgcn_rcpf(rs0) : (br == 1) ? rs0 * __builtin_amdgcn_rcpf(rs1) : (br == 2) ? rs1 : 1.f;
; #pragma unroll
;         for (int bj = 0; bj < 2; ++bj) {
;           u32x2 gnp[2], gdp[2];
;           unpair16(gw[g & 3][bj], gnp[0], gnp[1]); unpair16(dw[g & 3][bj], gdp[0], gdp[1]);
; #pragma unroll
;           for (int n = 0; n < 2; ++n) {
;             const f32x4 gn = unpack4(gnp[n]), gd = unpack4(gdp[n]);
;             f32x4 sc;
; #pragma unroll
;             for (int e = 0; e < 4; ++e) sc[e] = gn[e] * rsc * __builtin_amdgcn_rcpf(fmaxf(gd[e], 1e-30f));
;             acc[ai][bj][m][n] = acc[ai][bj][m][n] * sc;
;           }
;         }
;         if (br == 3) {
;           u16* mrow = MERGED + (size_t)row_ * 1024 + bcol + wc * 32;
;           store_pair16(mrow, pack4(acc[ai][0][m][0]), pack4(acc[ai][0][m][1]), fq);
;           store_pair16(mrow + 128, pack4(acc[ai][1][m][0]), pack4(acc[ai][1][m][1]), fq);
;         }
;         __builtin_amdgcn_sched_barrier(0);
;         if (g < 4) D_LOAD(g + 4, g & 3);
	v_pk_mul_f32 v[150:151], v[150:151], v[158:159]
	v_pk_mul_f32 v[106:107], v[106:107], v[144:145]
	v_pk_mul_f32 v[108:109], v[108:109], v[146:147]
	v_pk_mul_f32 v[114:115], v[114:115], v[148:149]
	v_pk_mul_f32 v[116:117], v[116:117], v[150:151]
	v_permlane16_swap_b32_e32 v236, v238
	v_permlane16_swap_b32_e32 v237, v239
	v_permlane16_swap_b32_e32 v228, v230
	v_permlane16_swap_b32_e32 v229, v231
	v_lshlrev_b32_e32 v152, 16, v236
	v_and_b32_e32 v153, 0xffff0000, v236
	v_lshlrev_b32_e32 v154, 16, v237
	v_and_b32_e32 v155, 0xffff0000, v237
	v_lshlrev_b32_e32 v156, 16, v238
	v_and_b32_e32 v157, 0xffff0000, v238
	v_lshlrev_b32_e32 v158, 16, v239
	v_and_b32_e32 v159, 0xffff0000, v239
	v_max_f32_e32 v152, 0xda24260, v152
	v_max_f32_e32 v153, 0xda24260, v153
	v_max_f32_e32 v154, 0xda24260, v154
	v_max_f32_e32 v155, 0xda24260, v155
	v_max_f32_e32 v156, 0xda24260, v156
	v_max_f32_e32 v157, 0xda24260, v157
	v_max_f32_e32 v158, 0xda24260, v158
	v_max_f32_e32 v159, 0xda24260, v159
	v_rcp_f32_e32 v152, v152
	v_rcp_f32_e32 v153, v153
	v_rcp_f32_e32 v154, v154
	v_rcp_f32_e32 v155, v155
	v_rcp_f32_e32 v156, v156
	v_rcp_f32_e32 v157, v157
	v_rcp_f32_e32 v158, v158
	v_rcp_f32_e32 v159, v159
	v_lshlrev_b32_e32 v144, 16, v228
	v_and_b32_e32 v145, 0xffff0000, v228
	v_lshlrev_b32_e32 v146, 16, v229
	v_and_b32_e32 v147, 0xffff0000, v229
	v_lshlrev_b32_e32 v148, 16, v230
	v_and_b32_e32 v149, 0xffff0000, v230
	v_lshlrev_b32_e32 v150, 16, v231
	v_and_b32_e32 v151, 0xffff0000, v231
	v_pk_mul_f32 v[144:145], v[164:165], v[144:145] op_sel_hi:[0,1]
	v_pk_mul_f32 v[146:147], v[164:165], v[146:147] op_sel_hi:[0,1]
	v_pk_mul_f32 v[148:149], v[164:165], v[148:149] op_sel_hi:[0,1]
	v_pk_mul_f32 v[150:151], v[164:165], v[150:151] op_sel_hi:[0,1]
	v_pk_mul_f32 v[144:145], v[144:145], v[152:153]
	v_pk_mul_f32 v[146:147], v[146:147], v[154:155]
	v_pk_mul_f32 v[148:149], v[148:149], v[156:157]
	v_pk_mul_f32 v[150:151], v[150:151], v[158:159]
	v_pk_mul_f32 v[118:119], v[118:119], v[144:145]
	v_pk_mul_f32 v[120:121], v[120:121], v[146:147]
	v_pk_mul_f32 v[126:127], v[126:127], v[148:149]
	v_pk_mul_f32 v[128:129], v[128:129], v[150:151]
	v_add_u32_e32 v138, 0xf0000, v132
	global_load_dwordx4 v[224:227], v138, s[56:57]
	global_load_dwordx4 v[228:231], v138, s[56:57] offset:256
	global_load_dwordx4 v[232:235], v138, s[62:63]
	global_load_dwordx4 v[236:239], v138, s[62:63] offset:256
	s_waitcnt vmcnt(20)
	v_permlane16_swap_b32_e32 v176, v178
	v_permlane16_swap_b32_e32 v177, v179
	v_permlane16_swap_b32_e32 v240, v242
	v_permlane16_swap_b32_e32 v241, v243
	v_lshlrev_b32_e32 v152, 16, v176
	v_and_b32_e32 v153, 0xffff0000, v176
	v_lshlrev_b32_e32 v154, 16, v177
	v_and_b32_e32 v155, 0xffff0000, v177
	v_lshlrev_b32_e32 v156, 16, v178
	v_and_b32_e32 v157, 0xffff0000, v178
	v_lshlrev_b32_e32 v158, 16, v179
	v_and_b32_e32 v159, 0xffff0000, v179
	v_max_f32_e32 v152, 0xda24260, v152
	v_max_f32_e32 v153, 0xda24260, v153
	v_max_f32_e32 v154, 0xda24260, v154
	v_max_f32_e32 v155, 0xda24260, v155
	v_max_f32_e32 v156, 0xda24260, v156
	v_max_f32_e32 v157, 0xda24260, v157
	v_max_f32_e32 v158, 0xda24260, v158
	v_max_f32_e32 v159, 0xda24260, v159
	v_rcp_f32_e32 v152, v152
	v_rcp_f32_e32 v153, v153
	v_rcp_f32_e32 v154, v154
	v_rcp_f32_e32 v155, v155
	v_rcp_f32_e32 v156, v156
	v_rcp_f32_e32 v157, v157
	v_rcp_f32_e32 v158, v158
	v_rcp_f32_e32 v159, v159
	v_lshlrev_b32_e32 v144, 16, v240
	v_and_b32_e32 v145, 0xffff0000, v240
	v_lshlrev_b32_e32 v146, 16, v241
	v_and_b32_e32 v147, 0xffff0000, v241
	v_lshlrev_b32_e32 v148, 16, v242
	v_and_b32_e32 v149, 0xffff0000, v242
	v_lshlrev_b32_e32 v150, 16, v243
	v_and_b32_e32 v151, 0xffff0000, v243
	v_pk_mul_f32 v[144:145], v[166:167], v[144:145] op_sel_hi:[0,1]
	v_pk_mul_f32 v[146:147], v[166:167], v[146:147] op_sel_hi:[0,1]
	v_pk_mul_f32 v[148:149], v[166:167], v[148:149] op_sel_hi:[0,1]
	v_pk_mul_f32 v[150:151], v[166:167], v[150:151] op_sel_hi:[0,1]
	v_pk_mul_f32 v[144:145], v[144:145], v[152:153]
	v_pk_mul_f32 v[146:147], v[146:147], v[154:155]
	v_pk_mul_f32 v[148:149], v[148:149], v[156:157]
	v_pk_mul_f32 v[150:151], v[150:151], v[158:159]
	v_pk_mul_f32 v[122:123], v[122:123], v[144:145]
	v_pk_mul_f32 v[124:125], v[124:125], v[146:147]
	v_pk_mul_f32 v[110:111], v[110:111], v[148:149]
	v_pk_mul_f32 v[112:113], v[112:113], v[150:151]
	v_permlane16_swap_b32_e32 v180, v182
	v_permlane16_swap_b32_e32 v181, v183
	v_permlane16_swap_b32_e32 v244, v246
	v_permlane16_swap_b32_e32 v245, v247
	v_lshlrev_b32_e32 v152, 16, v180
	v_and_b32_e32 v153, 0xffff0000, v180
	v_lshlrev_b32_e32 v154, 16, v181
	v_and_b32_e32 v155, 0xffff0000, v181
	v_lshlrev_b32_e32 v156, 16, v182
	v_and_b32_e32 v157, 0xffff0000, v182
	v_lshlrev_b32_e32 v158, 16, v183
	v_and_b32_e32 v159, 0xffff0000, v183
	v_max_f32_e32 v152, 0xda24260, v152
	v_max_f32_e32 v153, 0xda24260, v153
	v_max_f32_e32 v154, 0xda24260, v154
	v_max_f32_e32 v155, 0xda24260, v155
	v_max_f32_e32 v156, 0xda24260, v156
	v_max_f32_e32 v157, 0xda24260, v157
	v_max_f32_e32 v158, 0xda24260, v158
	v_max_f32_e32 v159, 0xda24260, v159
	v_rcp_f32_e32 v152, v152
	v_rcp_f32_e32 v153, v153
	v_rcp_f32_e32 v154, v154
	v_rcp_f32_e32 v155, v155
	v_rcp_f32_e32 v156, v156
	v_rcp_f32_e32 v157, v157
	v_rcp_f32_e32 v158, v158
	v_rcp_f32_e32 v159, v159
	v_lshlrev_b32_e32 v144, 16, v244
	v_and_b32_e32 v145, 0xffff0000, v244
	v_lshlrev_b32_e32 v146, 16, v245
	v_and_b32_e32 v147, 0xffff0000, v245
	v_lshlrev_b32_e32 v148, 16, v246
	v_and_b32_e32 v149, 0xffff0000, v246
	v_lshlrev_b32_e32 v150, 16, v247
	v_and_b32_e32 v151, 0xffff0000, v247
	v_pk_mul_f32 v[144:145], v[166:167], v[144:145] op_sel_hi:[0,1]
	v_pk_mul_f32 v[146:147], v[166:167], v[146:147] op_sel_hi:[0,1]
	v_pk_mul_f32 v[148:149], v[166:167], v[148:149] op_sel_hi:[0,1]
	v_pk_mul_f32 v[150:151], v[166:167], v[150:151] op_sel_hi:[0,1]
	v_pk_mul_f32 v[144:145], v[144:145], v[152:153]
	v_pk_mul_f32 v[146:147], v[146:147], v[154:155]
	v_pk_mul_f32 v[148:149], v[148:149], v[156:157]
	v_pk_mul_f32 v[150:151], v[150:151], v[158:159]
	v_pk_mul_f32 v[102:103], v[102:103], v[144:145]
	v_pk_mul_f32 v[104:105], v[104:105], v[146:147]
	v_pk_mul_f32 v[98:99], v[98:99], v[148:149]
	v_pk_mul_f32 v[100:101], v[100:101], v[150:151]
	v_add_u32_e32 v138, 0x108000, v132
	global_load_dwordx4 v[240:243], v138, s[56:57]
	global_load_dwordx4 v[244:247], v138, s[56:57] offset:256
	global_load_dwordx4 v[176:179], v138, s[62:63]
	global_load_dwordx4 v[180:183], v138, s[62:63] offset:256
	s_waitcnt vmcnt(12)
; __device__ __forceinline__ f32x4 unpack4(u32x2 w) { return (f32x4){bflo(w.x), bfhi(w.x), bflo(w.y), bfhi(w.y)}; }
; __device__ __forceinline__ void phaseD(const Params& p, const int wv, const int rep) {
;     ...
;       for (int g = 0; g < 8; ++g) {
;         __builtin_amdgcn_sched_barrier(0);
;         const int ai = g >> 2, m = g & 3, rrow = ai * 128 + wr * 64 + m * 16 + fr, row_ = brow + rrow;
;         const float rs0 = rs_l[rrow * 2], rs1 = rs_l[rrow * 2 + 1];
;         const float rsc = (br == 0) ? __builtin_amdgcn_rcpf(rs0) : (br == 1) ? rs0 * __builtin_amdgcn_rcpf(rs1) : (br == 2) ? rs1 : 1.f;
; #pragma unroll
;         for (int bj = 0; bj < 2; ++bj) {
;           u32x2 gnp[2], gdp[2];
;           unpair16(gw[g & 3][bj], gnp[0], gnp[1]); unpair16(dw[g & 3][bj], gdp[0], gdp[1]);
; #pragma unroll
;           for (int n = 0; n < 2; ++n) {
;             const f32x4 gn = unpack4(gnp[n]), gd = unpack4(gdp[n]);
;             f32x4 sc;
; #pragma unroll
;             for (int e = 0; e < 4; ++e) sc[e] = gn[e] * rsc * __builtin_amdgcn_rcpf(fmaxf(gd[e], 1e-30f));
;             acc[ai][bj][m][n] = acc[ai][bj][m][n] * sc;
;           }
;         }
	v_permlane16_swap_b32_e32 v200, v202
	v_permlane16_swap_b32_e32 v201, v203
	v_permlane16_swap_b32_e32 v192, v194
	v_permlane16_swap_b32_e32 v193, v195
	v_lshlrev_b32_e32 v152, 16, v200
	v_and_b32_e32 v153, 0xffff0000, v200
	v_lshlrev_b32_e32 v154, 16, v201
	v_and_b32_e32 v155, 0xffff0000, v201
	v_lshlrev_b32_e32 v156, 16, v202
	v_and_b32_e32 v157, 0xffff0000, v202
	v_lshlrev_b32_e32 v158, 16, v203
	v_and_b32_e32 v159, 0xffff0000, v203
	v_max_f32_e32 v152, 0xda24260, v152
	v_max_f32_e32 v153, 0xda24260, v153
	v_max_f32_e32 v154, 0xda24260, v154
	v_max_f32_e32 v155, 0xda24260, v155
	v_max_f32_e32 v156, 0xda24260, v156
	v_max_f32_e32 v157, 0xda24260, v157
	v_max_f32_e32 v158, 0xda24260, v158
	v_max_f32_e32 v159, 0xda24260, v159
	v_rcp_f32_e32 v152, v152
	v_rcp_f32_e32 v153, v153
	v_rcp_f32_e32 v154, v154
	v_rcp_f32_e32 v155, v155
	v_rcp_f32_e32 v156, v156
	v_rcp_f32_e32 v157, v157
	v_rcp_f32_e32 v158, v158
	v_rcp_f32_e32 v159, v159
	v_lshlrev_b32_e32 v144, 16, v192
	v_and_b32_e32 v145, 0xffff0000, v192
	v_lshlrev_b32_e32 v146, 16, v193
	v_and_b32_e32 v147, 0xffff0000, v193
	v_lshlrev_b32_e32 v148, 16, v194
	v_and_b32_e32 v149, 0xffff0000, v194
	v_lshlrev_b32_e32 v150, 16, v195
	v_and_b32_e32 v151, 0xffff0000, v195
	v_pk_mul_f32 v[144:145], v[168:169], v[144:145] op_sel_hi:[0,1]
	v_pk_mul_f32 v[146:147], v[168:169], v[146:147] op_sel_hi:[0,1]
	v_pk_mul_f32 v[148:149], v[168:169], v[148:149] op_sel_hi:[0,1]
	v_pk_mul_f32 v[150:151], v[168:169], v[150:151] op_sel_hi:[0,1]
	v_pk_mul_f32 v[144:145], v[144:145], v[152:153]
	v_pk_mul_f32 v[146:147], v[146:147], v[154:155]
	v_pk_mul_f32 v[148:149], v[148:149], v[156:157]
	v_pk_mul_f32 v[150:151], v[150:151], v[158:159]
	v_pk_mul_f32 v[94:95], v[94:95], v[144:145]
	v_pk_mul_f32 v[96:97], v[96:97], v[146:147]
	v_pk_mul_f32 v[86:87], v[86:87], v[148:149]
	v_pk_mul_f32 v[88:89], v[88:89], v[150:151]
	v_permlane16_swap_b32_e32 v204, v206
	v_permlane16_swap_b32_e32 v205, v207
	v_permlane16_swap_b32_e32 v196, v198
	v_permlane16_swap_b32_e32 v197, v199
	v_lshlrev_b32_e32 v152, 16, v204
	v_and_b32_e32 v153, 0xffff0000, v204
	v_lshlrev_b32_e32 v154, 16, v205
	v_and_b32_e32 v155, 0xffff0000, v205
	v_lshlrev_b32_e32 v156, 16, v206
	v_and_b32_e32 v157, 0xffff0000, v206
	v_lshlrev_b32_e32 v158, 16, v207
	v_and_b32_e32 v159, 0xffff0000, v207
	v_max_f32_e32 v152, 0xda24260, v152
	v_max_f32_e32 v153, 0xda24260, v153
	v_max_f32_e32 v154, 0xda24260, v154
	v_max_f32_e32 v155, 0xda24260, v155
	v_max_f32_e32 v156, 0xda24260, v156
	v_max_f32_e32 v157, 0xda24260, v157
	v_max_f32_e32 v158, 0xda24260, v158
	v_max_f32_e32 v159, 0xda24260, v159
	v_rcp_f32_e32 v152, v152
	v_rcp_f32_e32 v153, v153
	v_rcp_f32_e32 v154, v154
	v_rcp_f32_e32 v155, v155
	v_rcp_f32_e32 v156, v156
	v_rcp_f32_e32 v157, v157
	v_rcp_f32_e32 v158, v158
	v_rcp_f32_e32 v159, v159
	v_lshlrev_b32_e32 v144, 16, v196
	v_and_b32_e32 v145, 0xffff0000, v196
	v_lshlrev_b32_e32 v146, 16, v197
	v_and_b32_e32 v147, 0xffff0000, v197
	v_lshlrev_b32_e32 v148, 16, v198
	v_and_b32_e32 v149, 0xffff0000, v198
	v_lshlrev_b32_e32 v150, 16, v199
	v_and_b32_e32 v151, 0xffff0000, v199
	v_pk_mul_f32 v[144:145], v[168:169], v[144:145] op_sel_hi:[0,1]
	v_pk_mul_f32 v[146:147], v[168:169], v[146:147] op_sel_hi:[0,1]
	v_pk_mul_f32 v[148:149], v[168:169], v[148:149] op_sel_hi:[0,1]
	v_pk_mul_f32 v[150:151], v[168:169], v[150:151] op_sel_hi:[0,1]
	v_pk_mul_f32 v[144:145], v[144:145], v[152:153]
	v_pk_mul_f32 v[146:147], v[146:147], v[154:155]
	v_pk_mul_f32 v[148:149], v[148:149], v[156:157]
	v_pk_mul_f32 v[150:151], v[150:151], v[158:159]
	v_pk_mul_f32 v[74:75], v[74:75], v[144:145]
	v_pk_mul_f32 v[76:77], v[76:77], v[146:147]
	v_pk_mul_f32 v[66:67], v[66:67], v[148:149]
	v_pk_mul_f32 v[68:69], v[68:69], v[150:151]
	s_waitcnt vmcnt(8)
	v_permlane16_swap_b32_e32 v216, v218
	v_permlane16_swap_b32_e32 v217, v219
	v_permlane16_swap_b32_e32 v208, v210
	v_permlane16_swap_b32_e32 v209, v211
	v_lshlrev_b32_e32 v152, 16, v216
	v_and_b32_e32 v153, 0xffff0000, v216
	v_lshlrev_b32_e32 v154, 16, v217
	v_and_b32_e32 v155, 0xffff0000, v217
	v_lshlrev_b32_e32 v156, 16, v218
	v_and_b32_e32 v157, 0xffff0000, v218
	v_lshlrev_b32_e32 v158, 16, v219
	v_and_b32_e32 v159, 0xffff0000, v219
	v_max_f32_e32 v152, 0xda24260, v152
	v_max_f32_e32 v153, 0xda24260, v153
	v_max_f32_e32 v154, 0xda24260, v154
	v_max_f32_e32 v155, 0xda24260, v155
	v_max_f32_e32 v156, 0xda24260, v156
	v_max_f32_e32 v157, 0xda24260, v157
	v_max_f32_e32 v158, 0xda24260, v158
	v_max_f32_e32 v159, 0xda24260, v159
	v_rcp_f32_e32 v152, v152
	v_rcp_f32_e32 v153, v153
	v_rcp_f32_e32 v154, v154
	v_rcp_f32_e32 v155, v155
	v_rcp_f32_e32 v156, v156
	v_rcp_f32_e32 v157, v157
	v_rcp_f32_e32 v158, v158
	v_rcp_f32_e32 v159, v159
	v_lshlrev_b32_e32 v144, 16, v208
	v_and_b32_e32 v145, 0xffff0000, v208
	v_lshlrev_b32_e32 v146, 16, v209
	v_and_b32_e32 v147, 0xffff0000, v209
	v_lshlrev_b32_e32 v148, 16, v210
	v_and_b32_e32 v149, 0xffff0000, v210
	v_lshlrev_b32_e32 v150, 16, v211
	v_and_b32_e32 v151, 0xffff0000, v211
	v_pk_mul_f32 v[144:145], v[170:171], v[144:145] op_sel_hi:[0,1]
	v_pk_mul_f32 v[146:147], v[170:171], v[146:147] op_sel_hi:[0,1]
	v_pk_mul_f32 v[148:149], v[170:171], v[148:149] op_sel_hi:[0,1]
	v_pk_mul_f32 v[150:151], v[170:171], v[150:151] op_sel_hi:[0,1]
	v_pk_mul_f32 v[144:145], v[144:145], v[152:153]
	v_pk_mul_f32 v[146:147], v[146:147], v[154:155]
	v_pk_mul_f32 v[148:149], v[148:149], v[156:157]
	v_pk_mul_f32 v[150:151], v[150:151], v[158:159]
	v_pk_mul_f32 v[62:63], v[62:63], v[144:145]
	v_pk_mul_f32 v[64:65], v[64:65], v[146:147]
	v_pk_mul_f32 v[58:59], v[58:59], v[148:149]
	v_pk_mul_f32 v[60:61], v[60:61], v[150:151]
; __device__ __forceinline__ f32x4 unpack4(u32x2 w) { return (f32x4){bflo(w.x), bfhi(w.x), bflo(w.y), bfhi(w.y)}; }
; __device__ __forceinline__ void phaseD(const Params& p, const int wv, const int rep) {
;     ...
;       for (int g = 0; g < 8; ++g) {
;         __builtin_amdgcn_sched_barrier(0);
;         const int ai = g >> 2, m = g & 3, rrow = ai * 128 + wr * 64 + m * 16 + fr, row_ = brow + rrow;
;         const float rs0 = rs_l[rrow * 2], rs1 = rs_l[rrow * 2 + 1];
;         const float rsc = (br == 0) ? __builtin_amdgcn_rcpf(rs0) : (br == 1) ? rs0 * __builtin_amdgcn_rcpf(rs1) : (br == 2) ? rs1 : 1.f;
; #pragma unroll
;         for (int bj = 0; bj < 2; ++bj) {
;           u32x2 gnp[2], gdp[2];
;           unpair16(gw[g & 3][bj], gnp[0], gnp[1]); unpair16(dw[g & 3][bj], gdp[0], gdp[1]);
; #pragma unroll
;           for (int n = 0; n < 2; ++n) {
;             const f32x4 gn = unpack4(gnp[n]), gd = unpack4(gdp[n]);
;             f32x4 sc;
; #pragma unroll
;             for (int e = 0; e < 4; ++e) sc[e] = gn[e] * rsc * __builtin_amdgcn_rcpf(fmaxf(gd[e], 1e-30f));
;             acc[ai][bj][m][n] = acc[ai][bj][m][n] * sc;
;           }
;         }
	v_permlane16_swap_b32_e32 v220, v222
	v_permlane16_swap_b32_e32 v221, v223
	v_permlane16_swap_b32_e32 v212, v214
	v_permlane16_swap_b32_e32 v213, v215
	v_lshlrev_b32_e32 v152, 16, v220
	v_and_b32_e32 v153, 0xffff0000, v220
	v_lshlrev_b32_e32 v154, 16, v221
	v_and_b32_e32 v155, 0xffff0000, v221
	v_lshlrev_b32_e32 v156, 16, v222
	v_and_b32_e32 v157, 0xffff0000, v222
	v_lshlrev_b32_e32 v158, 16, v223
	v_and_b32_e32 v159, 0xffff0000, v223
	v_max_f32_e32 v152, 0xda24260, v152
	v_max_f32_e32 v153, 0xda24260, v153
	v_max_f32_e32 v154, 0xda24260, v154
	v_max_f32_e32 v155, 0xda24260, v155
	v_max_f32_e32 v156, 0xda24260, v156
	v_max_f32_e32 v157, 0xda24260, v157
	v_max_f32_e32 v158, 0xda24260, v158
	v_max_f32_e32 v159, 0xda24260, v159
	v_rcp_f32_e32 v152, v152
	v_rcp_f32_e32 v153, v153
	v_rcp_f32_e32 v154, v154
	v_rcp_f32_e32 v155, v155
	v_rcp_f32_e32 v156, v156
	v_rcp_f32_e32 v157, v157
	v_rcp_f32_e32 v158, v158
	v_rcp_f32_e32 v159, v159
	v_lshlrev_b32_e32 v144, 16, v212
	v_and_b32_e32 v145, 0xffff0000, v212
	v_lshlrev_b32_e32 v146, 16, v213
	v_and_b32_e32 v147, 0xffff0000, v213
	v_lshlrev_b32_e32 v148, 16, v214
	v_and_b32_e32 v149, 0xffff0000, v214
	v_lshlrev_b32_e32 v150, 16, v215
	v_and_b32_e32 v151, 0xffff0000, v215
	v_pk_mul_f32 v[144:145], v[170:171], v[144:145] op_sel_hi:[0,1]
	v_pk_mul_f32 v[146:147], v[170:171], v[146:147] op_sel_hi:[0,1]
	v_pk_mul_f32 v[148:149], v[170:171], v[148:149] op_sel_hi:[0,1]
	v_pk_mul_f32 v[150:151], v[170:171], v[150:151] op_sel_hi:[0,1]
	v_pk_mul_f32 v[144:145], v[144:145], v[152:153]
	v_pk_mul_f32 v[146:147], v[146:147], v[154:155]
	v_pk_mul_f32 v[148:149], v[148:149], v[156:157]
	v_pk_mul_f32 v[150:151], v[150:151], v[158:159]
	v_pk_mul_f32 v[54:55], v[54:55], v[144:145]
	v_pk_mul_f32 v[56:57], v[56:57], v[146:147]
	v_pk_mul_f32 v[50:51], v[50:51], v[148:149]
	v_pk_mul_f32 v[52:53], v[52:53], v[150:151]
	s_waitcnt vmcnt(4)
	v_permlane16_swap_b32_e32 v232, v234
	v_permlane16_swap_b32_e32 v233, v235
	v_permlane16_swap_b32_e32 v224, v226
	v_permlane16_swap_b32_e32 v225, v227
	v_lshlrev_b32_e32 v152, 16, v232
	v_and_b32_e32 v153, 0xffff0000, v232
	v_lshlrev_b32_e32 v154, 16, v233
	v_and_b32_e32 v155, 0xffff0000, v233
	v_lshlrev_b32_e32 v156, 16, v234
	v_and_b32_e32 v157, 0xffff0000, v234
	v_lshlrev_b32_e32 v158, 16, v235
	v_and_b32_e32 v159, 0xffff0000, v235
	v_max_f32_e32 v152, 0xda24260, v152
	v_max_f32_e32 v153, 0xda24260, v153
	v_max_f32_e32 v154, 0xda24260, v154
	v_max_f32_e32 v155, 0xda24260, v155
	v_max_f32_e32 v156, 0xda24260, v156
	v_max_f32_e32 v157, 0xda24260, v157
	v_max_f32_e32 v158, 0xda24260, v158
	v_max_f32_e32 v159, 0xda24260, v159
	v_rcp_f32_e32 v152, v152
	v_rcp_f32_e32 v153, v153
	v_rcp_f32_e32 v154, v154
	v_rcp_f32_e32 v155, v155
	v_rcp_f32_e32 v156, v156
	v_rcp_f32_e32 v157, v157
	v_rcp_f32_e32 v158, v158
	v_rcp_f32_e32 v159, v159
	v_lshlrev_b32_e32 v144, 16, v224
	v_and_b32_e32 v145, 0xffff0000, v224
	v_lshlrev_b32_e32 v146, 16, v225
	v_and_b32_e32 v147, 0xffff0000, v225
	v_lshlrev_b32_e32 v148, 16, v226
	v_and_b32_e32 v149, 0xffff0000, v226
	v_lshlrev_b32_e32 v150, 16, v227
	v_and_b32_e32 v151, 0xffff0000, v227
	v_pk_mul_f32 v[144:145], v[172:173], v[144:145] op_sel_hi:[0,1]
	v_pk_mul_f32 v[146:147], v[172:173], v[146:147] op_sel_hi:[0,1]
	v_pk_mul_f32 v[148:149], v[172:173], v[148:149] op_sel_hi:[0,1]
	v_pk_mul_f32 v[150:151], v[172:173], v[150:151] op_sel_hi:[0,1]
	v_pk_mul_f32 v[144:145], v[144:145], v[152:153]
	v_pk_mul_f32 v[146:147], v[146:147], v[154:155]
	v_pk_mul_f32 v[148:149], v[148:149], v[156:157]
	v_pk_mul_f32 v[150:151], v[150:151], v[158:159]
	v_pk_mul_f32 v[34:35], v[34:35], v[144:145]
	v_pk_mul_f32 v[36:37], v[36:37], v[146:147]
	v_pk_mul_f32 v[26:27], v[26:27], v[148:149]
	v_pk_mul_f32 v[28:29], v[28:29], v[150:151]
	v_permlane16_swap_b32_e32 v236, v238
	v_permlane16_swap_b32_e32 v237, v239
	v_permlane16_swap_b32_e32 v228, v230
	v_permlane16_swap_b32_e32 v229, v231
	v_lshlrev_b32_e32 v152, 16, v236
	v_and_b32_e32 v153, 0xffff0000, v236
	v_lshlrev_b32_e32 v154, 16, v237
	v_and_b32_e32 v155, 0xffff0000, v237
	v_lshlrev_b32_e32 v156, 16, v238
	v_and_b32_e32 v157, 0xffff0000, v238
	v_lshlrev_b32_e32 v158, 16, v239
	v_and_b32_e32 v159, 0xffff0000, v239
	v_max_f32_e32 v152, 0xda24260, v152
	v_max_f32_e32 v153, 0xda24260, v153
	v_max_f32_e32 v154, 0xda24260, v154
	v_max_f32_e32 v155, 0xda24260, v155
	v_max_f32_e32 v156, 0xda24260, v156
	v_max_f32_e32 v157, 0xda24260, v157
	v_max_f32_e32 v158, 0xda24260, v158
	v_max_f32_e32 v159, 0xda24260, v159
	v_rcp_f32_e32 v152, v152
	v_rcp_f32_e32 v153, v153
	v_rcp_f32_e32 v154, v154
	v_rcp_f32_e32 v155, v155
	v_rcp_f32_e32 v156, v156
	v_rcp_f32_e32 v157, v157
	v_rcp_f32_e32 v158, v158
	v_rcp_f32_e32 v159, v159
	v_lshlrev_b32_e32 v144, 16, v228
	v_and_b32_e32 v145, 0xffff0000, v228
	v_lshlrev_b32_e32 v146, 16, v229
	v_and_b32_e32 v147, 0xffff0000, v229
	v_lshlrev_b32_e32 v148, 16, v230
	v_and_b32_e32 v149, 0xffff0000, v230
	v_lshlrev_b32_e32 v150, 16, v231
	v_and_b32_e32 v151, 0xffff0000, v231
	v_pk_mul_f32 v[144:145], v[172:173], v[144:145] op_sel_hi:[0,1]
	v_pk_mul_f32 v[146:147], v[172:173], v[146:147] op_sel_hi:[0,1]
	v_pk_mul_f32 v[148:149], v[172:173], v[148:149] op_sel_hi:[0,1]
	v_pk_mul_f32 v[150:151], v[172:173], v[150:151] op_sel_hi:[0,1]
	v_pk_mul_f32 v[144:145], v[144:145], v[152:153]
	v_pk_mul_f32 v[146:147], v[146:147], v[154:155]
	v_pk_mul_f32 v[148:149], v[148:149], v[156:157]
	v_pk_mul_f32 v[150:151], v[150:151], v[158:159]
	v_pk_mul_f32 v[22:23], v[22:23], v[144:145]
	v_pk_mul_f32 v[24:25], v[24:25], v[146:147]
	v_pk_mul_f32 v[18:19], v[18:19], v[148:149]
	v_pk_mul_f32 v[20:21], v[20:21], v[150:151]
	s_waitcnt vmcnt(0)
; __device__ __forceinline__ u32x2 pack4(f32x4 v) { u32x2 r; r.x = cvt_pk(v[0], v[1]); r.y = cvt_pk(v[2], v[3]); return r; }
; __device__ __forceinline__ f32x4 unpack4(u32x2 w) { return (f32x4){bflo(w.x), bfhi(w.x), bflo(w.y), bfhi(w.y)}; }
; __device__ __forceinline__ int lane_fresh() { int l; asm volatile("v_mbcnt_lo_u32_b32 %0, -1, 0\n\tv_mbcnt_hi_u32_b32 %0, -1, %0" : "=v"(l)); return l; }
; __device__ __forceinline__ void phaseD(const Params& p, const int wv, const int rep) {
;     ...
;       const int gnum = (br == 0) ? 0 : (br == 2) ? 1024 : 2048, gden = (br == 0) ? 1024 : 2048;
;       const int lane_e = lane_fresh(), fr = lane_e & 15, fq = lane_e >> 4;
;       const int r0 = brow + wr * 64 + fr, c0 = bcol + wc * 32 + fq * 4;
;       u32x4 gw[4][2], dw[4][2];
;       const int poff = (fq & 1) * 16 + (fq >> 1) * 8;
;     ...
;       D_LOAD(0, 0); D_LOAD(1, 1); D_LOAD(2, 2); D_LOAD(3, 3);
;       if (br < 3) { const u16 *An, *Bn; int ldn; opnd(br + 1, An, Bn, ldn); kloop_t<1, false>(An, ldn, Bn, ldn, 512, acc, wv); }
; #pragma unroll
;       for (int g = 0; g < 8; ++g) {
;         __builtin_amdgcn_sched_barrier(0);
;         const int ai = g >> 2, m = g & 3, rrow = ai * 128 + wr * 64 + m * 16 + fr, row_ = brow + rrow;
;         const float rs0 = rs_l[rrow * 2], rs1 = rs_l[rrow * 2 + 1];
;         const float rsc = (br == 0) ? __builtin_amdgcn_rcpf(rs0) : (br == 1) ? rs0 * __builtin_amdgcn_rcpf(rs1) : (br == 2) ? rs1 : 1.f;
; #pragma unroll
;         for (int bj = 0; bj < 2; ++bj) {
;           u32x2 gnp[2], gdp[2];
;           unpair16(gw[g & 3][bj], gnp[0], gnp[1]); unpair16(dw[g & 3][bj], gdp[0], gdp[1]);
; #pragma unroll
;           for (int n = 0; n < 2; ++n) {
;             const f32x4 gn = unpack4(gnp[n]), gd = unpack4(gdp[n]);
;             f32x4 sc;
; #pragma unroll
;             for (int e = 0; e < 4; ++e) sc[e] = gn[e] * rsc * __builtin_amdgcn_rcpf(fmaxf(gd[e], 1e-30f));
;             acc[ai][bj][m][n] = acc[ai][bj][m][n] * sc;
;           }
;         }
;         if (br == 3) {
;           u16* mrow = MERGED + (size_t)row_ * 1024 + bcol + wc * 32;
;           store_pair16(mrow, pack4(acc[ai][0][m][0]), pack4(acc[ai][0][m][1]), fq);
;           store_pair16(mrow + 128, pack4(acc[ai][1][m][0]), pack4(acc[ai][1][m][1]), fq);
;         }
	v_permlane16_swap_b32_e32 v176, v178
	v_permlane16_swap_b32_e32 v177, v179
	v_permlane16_swap_b32_e32 v240, v242
	v_permlane16_swap_b32_e32 v241, v243
	v_lshlrev_b32_e32 v152, 16, v176
	v_and_b32_e32 v153, 0xffff0000, v176
	v_lshlrev_b32_e32 v154, 16, v177
	v_and_b32_e32 v155, 0xffff0000, v177
	v_lshlrev_b32_e32 v156, 16, v178
	v_and_b32_e32 v157, 0xffff0000, v178
	v_lshlrev_b32_e32 v158, 16, v179
	v_and_b32_e32 v159, 0xffff0000, v179
	v_max_f32_e32 v152, 0xda24260, v152
	v_max_f32_e32 v153, 0xda24260, v153
	v_max_f32_e32 v154, 0xda24260, v154
	v_max_f32_e32 v155, 0xda24260, v155
	v_max_f32_e32 v156, 0xda24260, v156
	v_max_f32_e32 v157, 0xda24260, v157
	v_max_f32_e32 v158, 0xda24260, v158
	v_max_f32_e32 v159, 0xda24260, v159
	v_rcp_f32_e32 v152, v152
	v_rcp_f32_e32 v153, v153
	v_rcp_f32_e32 v154, v154
	v_rcp_f32_e32 v155, v155
	v_rcp_f32_e32 v156, v156
	v_rcp_f32_e32 v157, v157
	v_rcp_f32_e32 v158, v158
	v_rcp_f32_e32 v159, v159
	v_lshlrev_b32_e32 v144, 16, v240
	v_and_b32_e32 v145, 0xffff0000, v240
	v_lshlrev_b32_e32 v146, 16, v241
	v_and_b32_e32 v147, 0xffff0000, v241
	v_lshlrev_b32_e32 v148, 16, v242
	v_and_b32_e32 v149, 0xffff0000, v242
	v_lshlrev_b32_e32 v150, 16, v243
	v_and_b32_e32 v151, 0xffff0000, v243
	v_pk_mul_f32 v[144:145], v[174:175], v[144:145] op_sel_hi:[0,1]
	v_pk_mul_f32 v[146:147], v[174:175], v[146:147] op_sel_hi:[0,1]
	v_pk_mul_f32 v[148:149], v[174:175], v[148:149] op_sel_hi:[0,1]
	v_pk_mul_f32 v[150:151], v[174:175], v[150:151] op_sel_hi:[0,1]
	v_pk_mul_f32 v[144:145], v[144:145], v[152:153]
	v_pk_mul_f32 v[146:147], v[146:147], v[154:155]
	v_pk_mul_f32 v[148:149], v[148:149], v[156:157]
	v_pk_mul_f32 v[150:151], v[150:151], v[158:159]
	v_pk_mul_f32 v[14:15], v[14:15], v[144:145]
	v_pk_mul_f32 v[16:17], v[16:17], v[146:147]
	v_pk_mul_f32 v[10:11], v[10:11], v[148:149]
	v_pk_mul_f32 v[12:13], v[12:13], v[150:151]
	v_permlane16_swap_b32_e32 v180, v182
	v_permlane16_swap_b32_e32 v181, v183
	v_permlane16_swap_b32_e32 v244, v246
	v_permlane16_swap_b32_e32 v245, v247
	v_lshlrev_b32_e32 v152, 16, v180
	v_and_b32_e32 v153, 0xffff0000, v180
	v_lshlrev_b32_e32 v154, 16, v181
	v_and_b32_e32 v155, 0xffff0000, v181
	v_lshlrev_b32_e32 v156, 16, v182
	v_and_b32_e32 v157, 0xffff0000, v182
	v_lshlrev_b32_e32 v158, 16, v183
	v_and_b32_e32 v159, 0xffff0000, v183
	v_max_f32_e32 v152, 0xda24260, v152
	v_max_f32_e32 v153, 0xda24260, v153
	v_max_f32_e32 v154, 0xda24260, v154
	v_max_f32_e32 v155, 0xda24260, v155
	v_max_f32_e32 v156, 0xda24260, v156
	v_max_f32_e32 v157, 0xda24260, v157
	v_max_f32_e32 v158, 0xda24260, v158
	v_max_f32_e32 v159, 0xda24260, v159
	v_rcp_f32_e32 v152, v152
	v_rcp_f32_e32 v153, v153
	v_rcp_f32_e32 v154, v154
	v_rcp_f32_e32 v155, v155
	v_rcp_f32_e32 v156, v156
	v_rcp_f32_e32 v157, v157
	v_rcp_f32_e32 v158, v158
	v_rcp_f32_e32 v159, v159
	v_lshlrev_b32_e32 v144, 16, v244
	v_and_b32_e32 v145, 0xffff0000, v244
	v_lshlrev_b32_e32 v146, 16, v245
	v_and_b32_e32 v147, 0xffff0000, v245
	v_lshlrev_b32_e32 v148, 16, v246
	v_and_b32_e32 v149, 0xffff0000, v246
	v_lshlrev_b32_e32 v150, 16, v247
	v_and_b32_e32 v151, 0xffff0000, v247
	v_pk_mul_f32 v[144:145], v[174:175], v[144:145] op_sel_hi:[0,1]
	v_pk_mul_f32 v[146:147], v[174:175], v[146:147] op_sel_hi:[0,1]
	v_pk_mul_f32 v[148:149], v[174:175], v[148:149] op_sel_hi:[0,1]
	v_pk_mul_f32 v[150:151], v[174:175], v[150:151] op_sel_hi:[0,1]
	v_pk_mul_f32 v[144:145], v[144:145], v[152:153]
	v_pk_mul_f32 v[146:147], v[146:147], v[154:155]
	v_pk_mul_f32 v[148:149], v[148:149], v[156:157]
	v_pk_mul_f32 v[150:151], v[150:151], v[158:159]
	v_pk_mul_f32 v[6:7], v[6:7], v[144:145]
	v_pk_mul_f32 v[8:9], v[8:9], v[146:147]
	v_pk_mul_f32 v[2:3], v[2:3], v[148:149]
	v_pk_mul_f32 v[4:5], v[4:5], v[150:151]
	s_branch .LBB0_691
.Ldm_br3:
	s_add_u32 s56, s52, 0x1000
	s_addc_u32 s57, s53, 0
	global_load_dwordx4 v[192:195], v132, s[56:57]
	global_load_dwordx4 v[196:199], v132, s[56:57] offset:256
	v_add_u32_e32 v138, 0x18000, v132
	global_load_dwordx4 v[200:203], v138, s[56:57]
	global_load_dwordx4 v[204:207], v138, s[56:57] offset:256
	v_add_u32_e32 v138, 0x30000, v132
	global_load_dwordx4 v[208:211], v138, s[56:57]
	global_load_dwordx4 v[212:215], v138, s[56:57] offset:256
	v_add_u32_e32 v138, 0x48000, v132
	global_load_dwordx4 v[216:219], v138, s[56:57]
	global_load_dwordx4 v[220:223], v138, s[56:57] offset:256
	v_add_u32_e32 v138, 0xc0000, v132
	global_load_dwordx4 v[224:227], v138, s[56:57]
	global_load_dwordx4 v[228:231], v138, s[56:57] offset:256
	v_add_u32_e32 v138, 0xd8000, v132
	global_load_dwordx4 v[232:235], v138, s[56:57]
	global_load_dwordx4 v[236:239], v138, s[56:57] offset:256
	v_add_u32_e32 v138, 0xf0000, v132
	global_load_dwordx4 v[240:243], v138, s[56:57]
	global_load_dwordx4 v[244:247], v138, s[56:57] offset:256
	v_add_u32_e32 v138, 0x108000, v132
	global_load_dwordx4 v[176:179], v138, s[56:57]
	global_load_dwordx4 v[180:183], v138, s[56:57] offset:256
	v_or_b32_e32 v141, s87, v136
	v_add_u32_e32 v139, s90, v141
	v_lshlrev_b32_e32 v139, 11, v139
	v_lshl_add_u32 v139, v137, 1, v139
	s_waitcnt vmcnt(14)
; __device__ __forceinline__ u32x2 pack4(f32x4 v) { u32x2 r; r.x = cvt_pk(v[0], v[1]); r.y = cvt_pk(v[2], v[3]); return r; }
; __device__ __forceinline__ f32x4 unpack4(u32x2 w) { return (f32x4){bflo(w.x), bfhi(w.x), bflo(w.y), bfhi(w.y)}; }
; __device__ __forceinline__ void phaseD(const Params& p, const int wv, const int rep) {
;     ...
;       for (int g = 0; g < 8; ++g) {
;         __builtin_amdgcn_sched_barrier(0);
;         const int ai = g >> 2, m = g & 3, rrow = ai * 128 + wr * 64 + m * 16 + fr, row_ = brow + rrow;
;         const float rs0 = rs_l[rrow * 2], rs1 = rs_l[rrow * 2 + 1];
;         const float rsc = (br == 0) ? __builtin_amdgcn_rcpf(rs0) : (br == 1) ? rs0 * __builtin_amdgcn_rcpf(rs1) : (br == 2) ? rs1 : 1.f;
; #pragma unroll
;         for (int bj = 0; bj < 2; ++bj) {
;           u32x2 gnp[2], gdp[2];
;           unpair16(gw[g & 3][bj], gnp[0], gnp[1]); unpair16(dw[g & 3][bj], gdp[0], gdp[1]);
; #pragma unroll
;           for (int n = 0; n < 2; ++n) {
;             const f32x4 gn = unpack4(gnp[n]), gd = unpack4(gdp[n]);
;             f32x4 sc;
; #pragma unroll
;             for (int e = 0; e < 4; ++e) sc[e] = gn[e] * rsc * __builtin_amdgcn_rcpf(fmaxf(gd[e], 1e-30f));
;             acc[ai][bj][m][n] = acc[ai][bj][m][n] * sc;
;           }
;         }
;         if (br == 3) {
;           u16* mrow = MERGED + (size_t)row_ * 1024 + bcol + wc * 32;
;           store_pair16(mrow, pack4(acc[ai][0][m][0]), pack4(acc[ai][0][m][1]), fq);
;           store_pair16(mrow + 128, pack4(acc[ai][1][m][0]), pack4(acc[ai][1][m][1]), fq);
;         }
	v_permlane16_swap_b32_e32 v192, v194
	v_permlane16_swap_b32_e32 v193, v195
	v_lshlrev_b32_e32 v144, 16, v192
	v_and_b32_e32 v145, 0xffff0000, v192
	v_lshlrev_b32_e32 v146, 16, v193
	v_and_b32_e32 v147, 0xffff0000, v193
	v_lshlrev_b32_e32 v148, 16, v194
	v_and_b32_e32 v149, 0xffff0000, v194
	v_lshlrev_b32_e32 v150, 16, v195
	v_and_b32_e32 v151, 0xffff0000, v195
	v_pk_mul_f32 v[30:31], v[30:31], v[144:145]
	v_pk_mul_f32 v[32:33], v[32:33], v[146:147]
	v_pk_mul_f32 v[38:39], v[38:39], v[148:149]
	v_pk_mul_f32 v[40:41], v[40:41], v[150:151]
	v_permlane16_swap_b32_e32 v196, v198
	v_permlane16_swap_b32_e32 v197, v199
	v_lshlrev_b32_e32 v144, 16, v196
	v_and_b32_e32 v145, 0xffff0000, v196
	v_lshlrev_b32_e32 v146, 16, v197
	v_and_b32_e32 v147, 0xffff0000, v197
	v_lshlrev_b32_e32 v148, 16, v198
	v_and_b32_e32 v149, 0xffff0000, v198
	v_lshlrev_b32_e32 v150, 16, v199
	v_and_b32_e32 v151, 0xffff0000, v199
	v_pk_mul_f32 v[42:43], v[42:43], v[144:145]
	v_pk_mul_f32 v[44:45], v[44:45], v[146:147]
	v_pk_mul_f32 v[46:47], v[46:47], v[148:149]
	v_pk_mul_f32 v[48:49], v[48:49], v[150:151]
	v_cvt_pk_bf16_f32 v152, v30, v31
	v_cvt_pk_bf16_f32 v153, v32, v33
	v_cvt_pk_bf16_f32 v154, v38, v39
	v_cvt_pk_bf16_f32 v155, v40, v41
	s_nop 1
	v_permlane16_swap_b32_e32 v152, v154
	v_permlane16_swap_b32_e32 v153, v155
	global_store_dwordx4 v139, v[152:155], s[54:55] sc1
	v_cvt_pk_bf16_f32 v156, v42, v43
	v_cvt_pk_bf16_f32 v157, v44, v45
	v_cvt_pk_bf16_f32 v158, v46, v47
	v_cvt_pk_bf16_f32 v159, v48, v49
	s_nop 1
	v_permlane16_swap_b32_e32 v156, v158
	v_permlane16_swap_b32_e32 v157, v159
	global_store_dwordx4 v139, v[156:159], s[54:55] offset:256 sc1
	s_waitcnt vmcnt(14)
	v_permlane16_swap_b32_e32 v200, v202
	v_permlane16_swap_b32_e32 v201, v203
	v_lshlrev_b32_e32 v144, 16, v200
	v_and_b32_e32 v145, 0xffff0000, v200
	v_lshlrev_b32_e32 v146, 16, v201
	v_and_b32_e32 v147, 0xffff0000, v201
	v_lshlrev_b32_e32 v148, 16, v202
	v_and_b32_e32 v149, 0xffff0000, v202
	v_lshlrev_b32_e32 v150, 16, v203
	v_and_b32_e32 v151, 0xffff0000, v203
	v_pk_mul_f32 v[70:71], v[70:71], v[144:145]
	v_pk_mul_f32 v[72:73], v[72:73], v[146:147]
	v_pk_mul_f32 v[78:79], v[78:79], v[148:149]
	v_pk_mul_f32 v[80:81], v[80:81], v[150:151]
	v_permlane16_swap_b32_e32 v204, v206
	v_permlane16_swap_b32_e32 v205, v207
	v_lshlrev_b32_e32 v144, 16, v204
	v_and_b32_e32 v145, 0xffff0000, v204
	v_lshlrev_b32_e32 v146, 16, v205
	v_and_b32_e32 v147, 0xffff0000, v205
	v_lshlrev_b32_e32 v148, 16, v206
	v_and_b32_e32 v149, 0xffff0000, v206
	v_lshlrev_b32_e32 v150, 16, v207
	v_and_b32_e32 v151, 0xffff0000, v207
	v_pk_mul_f32 v[82:83], v[82:83], v[144:145]
	v_pk_mul_f32 v[84:85], v[84:85], v[146:147]
	v_pk_mul_f32 v[90:91], v[90:91], v[148:149]
	v_pk_mul_f32 v[92:93], v[92:93], v[150:151]
	v_add_u32_e32 v138, 0x8000, v139
	v_cvt_pk_bf16_f32 v152, v70, v71
	v_cvt_pk_bf16_f32 v153, v72, v73
	v_cvt_pk_bf16_f32 v154, v78, v79
	v_cvt_pk_bf16_f32 v155, v80, v81
	s_nop 1
	v_permlane16_swap_b32_e32 v152, v154
	v_permlane16_swap_b32_e32 v153, v155
	global_store_dwordx4 v138, v[152:155], s[54:55] sc1
	v_cvt_pk_bf16_f32 v156, v82, v83
	v_cvt_pk_bf16_f32 v157, v84, v85
	v_cvt_pk_bf16_f32 v158, v90, v91
	v_cvt_pk_bf16_f32 v159, v92, v93
	s_nop 1
	v_permlane16_swap_b32_e32 v156, v158
	v_permlane16_swap_b32_e32 v157, v159
	global_store_dwordx4 v138, v[156:159], s[54:55] offset:256 sc1
	s_waitcnt vmcnt(14)
	v_permlane16_swap_b32_e32 v208, v210
	v_permlane16_swap_b32_e32 v209, v211
	v_lshlrev_b32_e32 v144, 16, v208
	v_and_b32_e32 v145, 0xffff0000, v208
	v_lshlrev_b32_e32 v146, 16, v209
	v_and_b32_e32 v147, 0xffff0000, v209
	v_lshlrev_b32_e32 v148, 16, v210
	v_and_b32_e32 v149, 0xffff0000, v210
	v_lshlrev_b32_e32 v150, 16, v211
	v_and_b32_e32 v151, 0xffff0000, v211
	v_pk_mul_f32 v[106:107], v[106:107], v[144:145]
	v_pk_mul_f32 v[108:109], v[108:109], v[146:147]
	v_pk_mul_f32 v[114:115], v[114:115], v[148:149]
	v_pk_mul_f32 v[116:117], v[116:117], v[150:151]
	v_permlane16_swap_b32_e32 v212, v214
	v_permlane16_swap_b32_e32 v213, v215
	v_lshlrev_b32_e32 v144, 16, v212
	v_and_b32_e32 v145, 0xffff0000, v212
	v_lshlrev_b32_e32 v146, 16, v213
	v_and_b32_e32 v147, 0xffff0000, v213
	v_lshlrev_b32_e32 v148, 16, v214
	v_and_b32_e32 v149, 0xffff0000, v214
	v_lshlrev_b32_e32 v150, 16, v215
	v_and_b32_e32 v151, 0xffff0000, v215
	v_pk_mul_f32 v[118:119], v[118:119], v[144:145]
	v_pk_mul_f32 v[120:121], v[120:121], v[146:147]
	v_pk_mul_f32 v[126:127], v[126:127], v[148:149]
	v_pk_mul_f32 v[128:129], v[128:129], v[150:151]
	v_add_u32_e32 v138, 0x10000, v139
	v_cvt_pk_bf16_f32 v152, v106, v107
	v_cvt_pk_bf16_f32 v153, v108, v109
	v_cvt_pk_bf16_f32 v154, v114, v115
	v_cvt_pk_bf16_f32 v155, v116, v117
	s_nop 1
	v_permlane16_swap_b32_e32 v152, v154
	v_permlane16_swap_b32_e32 v153, v155
	global_store_dwordx4 v138, v[152:155], s[54:55] sc1
	v_cvt_pk_bf16_f32 v156, v118, v119
	v_cvt_pk_bf16_f32 v157, v120, v121
	v_cvt_pk_bf16_f32 v158, v126, v127
	v_cvt_pk_bf16_f32 v159, v128, v129
	s_nop 1
	v_permlane16_swap_b32_e32 v156, v158
	v_permlane16_swap_b32_e32 v157, v159
	global_store_dwordx4 v138, v[156:159], s[54:55] offset:256 sc1
	s_waitcnt vmcnt(14)
; __device__ __forceinline__ u32x2 pack4(f32x4 v) { u32x2 r; r.x = cvt_pk(v[0], v[1]); r.y = cvt_pk(v[2], v[3]); return r; }
; __device__ __forceinline__ f32x4 unpack4(u32x2 w) { return (f32x4){bflo(w.x), bfhi(w.x), bflo(w.y), bfhi(w.y)}; }
; __device__ __forceinline__ void phaseD(const Params& p, const int wv, const int rep) {
;     ...
;       for (int g = 0; g < 8; ++g) {
;         __builtin_amdgcn_sched_barrier(0);
;         const int ai = g >> 2, m = g & 3, rrow = ai * 128 + wr * 64 + m * 16 + fr, row_ = brow + rrow;
;         const float rs0 = rs_l[rrow * 2], rs1 = rs_l[rrow * 2 + 1];
;         const float rsc = (br == 0) ? __builtin_amdgcn_rcpf(rs0) : (br == 1) ? rs0 * __builtin_amdgcn_rcpf(rs1) : (br == 2) ? rs1 : 1.f;
; #pragma unroll
;         for (int bj = 0; bj < 2; ++bj) {
;           u32x2 gnp[2], gdp[2];
;           unpair16(gw[g & 3][bj], gnp[0], gnp[1]); unpair16(dw[g & 3][bj], gdp[0], gdp[1]);
; #pragma unroll
;           for (int n = 0; n < 2; ++n) {
;             const f32x4 gn = unpack4(gnp[n]), gd = unpack4(gdp[n]);
;             f32x4 sc;
; #pragma unroll
;             for (int e = 0; e < 4; ++e) sc[e] = gn[e] * rsc * __builtin_amdgcn_rcpf(fmaxf(gd[e], 1e-30f));
;             acc[ai][bj][m][n] = acc[ai][bj][m][n] * sc;
;           }
;         }
;         if (br == 3) {
;           u16* mrow = MERGED + (size_t)row_ * 1024 + bcol + wc * 32;
;           store_pair16(mrow, pack4(acc[ai][0][m][0]), pack4(acc[ai][0][m][1]), fq);
;           store_pair16(mrow + 128, pack4(acc[ai][1][m][0]), pack4(acc[ai][1][m][1]), fq);
;         }
	v_permlane16_swap_b32_e32 v216, v218
	v_permlane16_swap_b32_e32 v217, v219
	v_lshlrev_b32_e32 v144, 16, v216
	v_and_b32_e32 v145, 0xffff0000, v216
	v_lshlrev_b32_e32 v146, 16, v217
	v_and_b32_e32 v147, 0xffff0000, v217
	v_lshlrev_b32_e32 v148, 16, v218
	v_and_b32_e32 v149, 0xffff0000, v218
	v_lshlrev_b32_e32 v150, 16, v219
	v_and_b32_e32 v151, 0xffff0000, v219
	v_pk_mul_f32 v[122:123], v[122:123], v[144:145]
	v_pk_mul_f32 v[124:125], v[124:125], v[146:147]
	v_pk_mul_f32 v[110:111], v[110:111], v[148:149]
	v_pk_mul_f32 v[112:113], v[112:113], v[150:151]
	v_permlane16_swap_b32_e32 v220, v222
	v_permlane16_swap_b32_e32 v221, v223
	v_lshlrev_b32_e32 v144, 16, v220
	v_and_b32_e32 v145, 0xffff0000, v220
	v_lshlrev_b32_e32 v146, 16, v221
	v_and_b32_e32 v147, 0xffff0000, v221
	v_lshlrev_b32_e32 v148, 16, v222
	v_and_b32_e32 v149, 0xffff0000, v222
	v_lshlrev_b32_e32 v150, 16, v223
	v_and_b32_e32 v151, 0xffff0000, v223
	v_pk_mul_f32 v[102:103], v[102:103], v[144:145]
	v_pk_mul_f32 v[104:105], v[104:105], v[146:147]
	v_pk_mul_f32 v[98:99], v[98:99], v[148:149]
	v_pk_mul_f32 v[100:101], v[100:101], v[150:151]
	v_add_u32_e32 v138, 0x18000, v139
	v_cvt_pk_bf16_f32 v152, v122, v123
	v_cvt_pk_bf16_f32 v153, v124, v125
	v_cvt_pk_bf16_f32 v154, v110, v111
	v_cvt_pk_bf16_f32 v155, v112, v113
	s_nop 1
	v_permlane16_swap_b32_e32 v152, v154
	v_permlane16_swap_b32_e32 v153, v155
	global_store_dwordx4 v138, v[152:155], s[54:55] sc1
	v_cvt_pk_bf16_f32 v156, v102, v103
	v_cvt_pk_bf16_f32 v157, v104, v105
	v_cvt_pk_bf16_f32 v158, v98, v99
	v_cvt_pk_bf16_f32 v159, v100, v101
	s_nop 1
	v_permlane16_swap_b32_e32 v156, v158
	v_permlane16_swap_b32_e32 v157, v159
	global_store_dwordx4 v138, v[156:159], s[54:55] offset:256 sc1
	s_waitcnt vmcnt(14)
	v_permlane16_swap_b32_e32 v224, v226
	v_permlane16_swap_b32_e32 v225, v227
	v_lshlrev_b32_e32 v144, 16, v224
	v_and_b32_e32 v145, 0xffff0000, v224
	v_lshlrev_b32_e32 v146, 16, v225
	v_and_b32_e32 v147, 0xffff0000, v225
	v_lshlrev_b32_e32 v148, 16, v226
	v_and_b32_e32 v149, 0xffff0000, v226
	v_lshlrev_b32_e32 v150, 16, v227
	v_and_b32_e32 v151, 0xffff0000, v227
	v_pk_mul_f32 v[94:95], v[94:95], v[144:145]
	v_pk_mul_f32 v[96:97], v[96:97], v[146:147]
	v_pk_mul_f32 v[86:87], v[86:87], v[148:149]
	v_pk_mul_f32 v[88:89], v[88:89], v[150:151]
	v_permlane16_swap_b32_e32 v228, v230
	v_permlane16_swap_b32_e32 v229, v231
	v_lshlrev_b32_e32 v144, 16, v228
	v_and_b32_e32 v145, 0xffff0000, v228
	v_lshlrev_b32_e32 v146, 16, v229
	v_and_b32_e32 v147, 0xffff0000, v229
	v_lshlrev_b32_e32 v148, 16, v230
	v_and_b32_e32 v149, 0xffff0000, v230
	v_lshlrev_b32_e32 v150, 16, v231
	v_and_b32_e32 v151, 0xffff0000, v231
	v_pk_mul_f32 v[74:75], v[74:75], v[144:145]
	v_pk_mul_f32 v[76:77], v[76:77], v[146:147]
	v_pk_mul_f32 v[66:67], v[66:67], v[148:149]
	v_pk_mul_f32 v[68:69], v[68:69], v[150:151]
	v_add_u32_e32 v138, 0x40000, v139
	v_cvt_pk_bf16_f32 v152, v94, v95
	v_cvt_pk_bf16_f32 v153, v96, v97
	v_cvt_pk_bf16_f32 v154, v86, v87
	v_cvt_pk_bf16_f32 v155, v88, v89
	s_nop 1
	v_permlane16_swap_b32_e32 v152, v154
	v_permlane16_swap_b32_e32 v153, v155
	global_store_dwordx4 v138, v[152:155], s[54:55] sc1
	v_cvt_pk_bf16_f32 v156, v74, v75
	v_cvt_pk_bf16_f32 v157, v76, v77
	v_cvt_pk_bf16_f32 v158, v66, v67
	v_cvt_pk_bf16_f32 v159, v68, v69
	s_nop 1
	v_permlane16_swap_b32_e32 v156, v158
	v_permlane16_swap_b32_e32 v157, v159
	global_store_dwordx4 v138, v[156:159], s[54:55] offset:256 sc1
	s_waitcnt vmcnt(14)
	v_permlane16_swap_b32_e32 v232, v234
	v_permlane16_swap_b32_e32 v233, v235
	v_lshlrev_b32_e32 v144, 16, v232
	v_and_b32_e32 v145, 0xffff0000, v232
	v_lshlrev_b32_e32 v146, 16, v233
	v_and_b32_e32 v147, 0xffff0000, v233
	v_lshlrev_b32_e32 v148, 16, v234
	v_and_b32_e32 v149, 0xffff0000, v234
	v_lshlrev_b32_e32 v150, 16, v235
	v_and_b32_e32 v151, 0xffff0000, v235
	v_pk_mul_f32 v[62:63], v[62:63], v[144:145]
	v_pk_mul_f32 v[64:65], v[64:65], v[146:147]
	v_pk_mul_f32 v[58:59], v[58:59], v[148:149]
	v_pk_mul_f32 v[60:61], v[60:61], v[150:151]
	v_permlane16_swap_b32_e32 v236, v238
	v_permlane16_swap_b32_e32 v237, v239
	v_lshlrev_b32_e32 v144, 16, v236
	v_and_b32_e32 v145, 0xffff0000, v236
	v_lshlrev_b32_e32 v146, 16, v237
	v_and_b32_e32 v147, 0xffff0000, v237
	v_lshlrev_b32_e32 v148, 16, v238
	v_and_b32_e32 v149, 0xffff0000, v238
	v_lshlrev_b32_e32 v150, 16, v239
	v_and_b32_e32 v151, 0xffff0000, v239
	v_pk_mul_f32 v[54:55], v[54:55], v[144:145]
	v_pk_mul_f32 v[56:57], v[56:57], v[146:147]
	v_pk_mul_f32 v[50:51], v[50:51], v[148:149]
	v_pk_mul_f32 v[52:53], v[52:53], v[150:151]
	v_add_u32_e32 v138, 0x48000, v139
	v_cvt_pk_bf16_f32 v152, v62, v63
	v_cvt_pk_bf16_f32 v153, v64, v65
	v_cvt_pk_bf16_f32 v154, v58, v59
	v_cvt_pk_bf16_f32 v155, v60, v61
	s_nop 1
	v_permlane16_swap_b32_e32 v152, v154
	v_permlane16_swap_b32_e32 v153, v155
	global_store_dwordx4 v138, v[152:155], s[54:55] sc1
	v_cvt_pk_bf16_f32 v156, v54, v55
	v_cvt_pk_bf16_f32 v157, v56, v57
	v_cvt_pk_bf16_f32 v158, v50, v51
	v_cvt_pk_bf16_f32 v159, v52, v53
	s_nop 1
	v_permlane16_swap_b32_e32 v156, v158
	v_permlane16_swap_b32_e32 v157, v159
	global_store_dwordx4 v138, v[156:159], s[54:55] offset:256 sc1
	s_waitcnt vmcnt(14)
; __device__ __forceinline__ u32x2 pack4(f32x4 v) { u32x2 r; r.x = cvt_pk(v[0], v[1]); r.y = cvt_pk(v[2], v[3]); return r; }
; __device__ __forceinline__ f32x4 unpack4(u32x2 w) { return (f32x4){bflo(w.x), bfhi(w.x), bflo(w.y), bfhi(w.y)}; }
; __device__ __forceinline__ void phaseD(const Params& p, const int wv, const int rep) {
;     ...
;       for (int g = 0; g < 8; ++g) {
;         __builtin_amdgcn_sched_barrier(0);
;         const int ai = g >> 2, m = g & 3, rrow = ai * 128 + wr * 64 + m * 16 + fr, row_ = brow + rrow;
;         const float rs0 = rs_l[rrow * 2], rs1 = rs_l[rrow * 2 + 1];
;         const float rsc = (br == 0) ? __builtin_amdgcn_rcpf(rs0) : (br == 1) ? rs0 * __builtin_amdgcn_rcpf(rs1) : (br == 2) ? rs1 : 1.f;
; #pragma unroll
;         for (int bj = 0; bj < 2; ++bj) {
;           u32x2 gnp[2], gdp[2];
;           unpair16(gw[g & 3][bj], gnp[0], gnp[1]); unpair16(dw[g & 3][bj], gdp[0], gdp[1]);
; #pragma unroll
;           for (int n = 0; n < 2; ++n) {
;             const f32x4 gn = unpack4(gnp[n]), gd = unpack4(gdp[n]);
;             f32x4 sc;
; #pragma unroll
;             for (int e = 0; e < 4; ++e) sc[e] = gn[e] * rsc * __builtin_amdgcn_rcpf(fmaxf(gd[e], 1e-30f));
;             acc[ai][bj][m][n] = acc[ai][bj][m][n] * sc;
;           }
;         }
;         if (br == 3) {
;           u16* mrow = MERGED + (size_t)row_ * 1024 + bcol + wc * 32;
;           store_pair16(mrow, pack4(acc[ai][0][m][0]), pack4(acc[ai][0][m][1]), fq);
;           store_pair16(mrow + 128, pack4(acc[ai][1][m][0]), pack4(acc[ai][1][m][1]), fq);
;         }
	v_permlane16_swap_b32_e32 v240, v242
	v_permlane16_swap_b32_e32 v241, v243
	v_lshlrev_b32_e32 v144, 16, v240
	v_and_b32_e32 v145, 0xffff0000, v240
	v_lshlrev_b32_e32 v146, 16, v241
	v_and_b32_e32 v147, 0xffff0000, v241
	v_lshlrev_b32_e32 v148, 16, v242
	v_and_b32_e32 v149, 0xffff0000, v242
	v_lshlrev_b32_e32 v150, 16, v243
	v_and_b32_e32 v151, 0xffff0000, v243
	v_pk_mul_f32 v[34:35], v[34:35], v[144:145]
	v_pk_mul_f32 v[36:37], v[36:37], v[146:147]
	v_pk_mul_f32 v[26:27], v[26:27], v[148:149]
	v_pk_mul_f32 v[28:29], v[28:29], v[150:151]
	v_permlane16_swap_b32_e32 v244, v246
	v_permlane16_swap_b32_e32 v245, v247
	v_lshlrev_b32_e32 v144, 16, v244
	v_and_b32_e32 v145, 0xffff0000, v244
	v_lshlrev_b32_e32 v146, 16, v245
	v_and_b32_e32 v147, 0xffff0000, v245
	v_lshlrev_b32_e32 v148, 16, v246
	v_and_b32_e32 v149, 0xffff0000, v246
	v_lshlrev_b32_e32 v150, 16, v247
	v_and_b32_e32 v151, 0xffff0000, v247
	v_pk_mul_f32 v[22:23], v[22:23], v[144:145]
	v_pk_mul_f32 v[24:25], v[24:25], v[146:147]
	v_pk_mul_f32 v[18:19], v[18:19], v[148:149]
	v_pk_mul_f32 v[20:21], v[20:21], v[150:151]
	v_add_u32_e32 v138, 0x50000, v139
	v_cvt_pk_bf16_f32 v152, v34, v35
	v_cvt_pk_bf16_f32 v153, v36, v37
	v_cvt_pk_bf16_f32 v154, v26, v27
	v_cvt_pk_bf16_f32 v155, v28, v29
	s_nop 1
	v_permlane16_swap_b32_e32 v152, v154
	v_permlane16_swap_b32_e32 v153, v155
	global_store_dwordx4 v138, v[152:155], s[54:55] sc1
	v_cvt_pk_bf16_f32 v156, v22, v23
	v_cvt_pk_bf16_f32 v157, v24, v25
	v_cvt_pk_bf16_f32 v158, v18, v19
	v_cvt_pk_bf16_f32 v159, v20, v21
	s_nop 1
	v_permlane16_swap_b32_e32 v156, v158
	v_permlane16_swap_b32_e32 v157, v159
	global_store_dwordx4 v138, v[156:159], s[54:55] offset:256 sc1
	s_waitcnt vmcnt(14)
	v_permlane16_swap_b32_e32 v176, v178
	v_permlane16_swap_b32_e32 v177, v179
	v_lshlrev_b32_e32 v144, 16, v176
	v_and_b32_e32 v145, 0xffff0000, v176
	v_lshlrev_b32_e32 v146, 16, v177
	v_and_b32_e32 v147, 0xffff0000, v177
	v_lshlrev_b32_e32 v148, 16, v178
	v_and_b32_e32 v149, 0xffff0000, v178
	v_lshlrev_b32_e32 v150, 16, v179
	v_and_b32_e32 v151, 0xffff0000, v179
	v_pk_mul_f32 v[14:15], v[14:15], v[144:145]
	v_pk_mul_f32 v[16:17], v[16:17], v[146:147]
	v_pk_mul_f32 v[10:11], v[10:11], v[148:149]
	v_pk_mul_f32 v[12:13], v[12:13], v[150:151]
	v_permlane16_swap_b32_e32 v180, v182
	v_permlane16_swap_b32_e32 v181, v183
	v_lshlrev_b32_e32 v144, 16, v180
	v_and_b32_e32 v145, 0xffff0000, v180
	v_lshlrev_b32_e32 v146, 16, v181
	v_and_b32_e32 v147, 0xffff0000, v181
	v_lshlrev_b32_e32 v148, 16, v182
	v_and_b32_e32 v149, 0xffff0000, v182
	v_lshlrev_b32_e32 v150, 16, v183
	v_and_b32_e32 v151, 0xffff0000, v183
	v_pk_mul_f32 v[6:7], v[6:7], v[144:145]
	v_pk_mul_f32 v[8:9], v[8:9], v[146:147]
	v_pk_mul_f32 v[2:3], v[2:3], v[148:149]
	v_pk_mul_f32 v[4:5], v[4:5], v[150:151]
	v_add_u32_e32 v138, 0x58000, v139
	v_cvt_pk_bf16_f32 v152, v14, v15
	v_cvt_pk_bf16_f32 v153, v16, v17
	v_cvt_pk_bf16_f32 v154, v10, v11
	v_cvt_pk_bf16_f32 v155, v12, v13
	s_nop 1
	v_permlane16_swap_b32_e32 v152, v154
	v_permlane16_swap_b32_e32 v153, v155
	global_store_dwordx4 v138, v[152:155], s[54:55] sc1
	v_cvt_pk_bf16_f32 v156, v6, v7
	v_cvt_pk_bf16_f32 v157, v8, v9
	v_cvt_pk_bf16_f32 v158, v2, v3
	v_cvt_pk_bf16_f32 v159, v4, v5
	s_nop 1
	v_permlane16_swap_b32_e32 v156, v158
	v_permlane16_swap_b32_e32 v157, v159
	global_store_dwordx4 v138, v[156:159], s[54:55] offset:256 sc1
	s_branch .LBB0_691
.Ldm_br1:
	ds_read_b64 v[160:161], v133
	ds_read_b64 v[162:163], v133 offset:128
	ds_read_b64 v[164:165], v133 offset:256
	ds_read_b64 v[166:167], v133 offset:384
	ds_read_b64 v[168:169], v133 offset:1024
	ds_read_b64 v[170:171], v133 offset:1152
	ds_read_b64 v[172:173], v133 offset:1280
	ds_read_b64 v[174:175], v133 offset:1408

; __device__ __forceinline__ f32x4 unpack4(u32x2 w) { return (f32x4){bflo(w.x), bfhi(w.x), bflo(w.y), bfhi(w.y)}; }
; __device__ __forceinline__ void phaseD(const Params& p, const int wv, const int rep) {
;     ...
;       for (int g = 0; g < 8; ++g) {
;         __builtin_amdgcn_sched_barrier(0);
;         const int ai = g >> 2, m = g & 3, rrow = ai * 128 + wr * 64 + m * 16 + fr, row_ = brow + rrow;
;         const float rs0 = rs_l[rrow * 2], rs1 = rs_l[rrow * 2 + 1];
;         const float rsc = (br == 0) ? __builtin_amdgcn_rcpf(rs0) : (br == 1) ? rs0 * __builtin_amdgcn_rcpf(rs1) : (br == 2) ? rs1 : 1.f;
; #pragma unroll
;         for (int bj = 0; bj < 2; ++bj) {
;           u32x2 gnp[2], gdp[2];
;           unpair16(gw[g & 3][bj], gnp[0], gnp[1]); unpair16(dw[g & 3][bj], gdp[0], gdp[1]);
; #pragma unroll
;           for (int n = 0; n < 2; ++n) {
;             const f32x4 gn = unpack4(gnp[n]), gd = unpack4(gdp[n]);
;             f32x4 sc;
; #pragma unroll
;             for (int e = 0; e < 4; ++e) sc[e] = gn[e] * rsc * __builtin_amdgcn_rcpf(fmaxf(gd[e], 1e-30f));
;             acc[ai][bj][m][n] = acc[ai][bj][m][n] * sc;
;           }
;         }
.Ldm1_775:
	s_waitcnt lgkmcnt(0)
	v_rcp_f32_e32 v161, v161
	v_rcp_f32_e32 v163, v163
	v_rcp_f32_e32 v165, v165
	v_rcp_f32_e32 v167, v167
	v_rcp_f32_e32 v169, v169
	v_rcp_f32_e32 v171, v171
	v_rcp_f32_e32 v173, v173
	v_rcp_f32_e32 v175, v175
	s_nop 0
	v_mul_f32_e32 v160, v160, v161
	v_mul_f32_e32 v162, v162, v163
	v_mul_f32_e32 v164, v164, v165
	v_mul_f32_e32 v166, v166, v167
	v_mul_f32_e32 v168, v168, v169
	v_mul_f32_e32 v170, v170, v171
	v_mul_f32_e32 v172, v172, v173
	v_mul_f32_e32 v174, v174, v175
	v_pk_mul_f32 v[30:31], v[160:161], v[30:31] op_sel_hi:[0,1]
	v_pk_mul_f32 v[32:33], v[160:161], v[32:33] op_sel_hi:[0,1]
	v_pk_mul_f32 v[38:39], v[160:161], v[38:39] op_sel_hi:[0,1]
	v_pk_mul_f32 v[40:41], v[160:161], v[40:41] op_sel_hi:[0,1]
	v_pk_mul_f32 v[42:43], v[160:161], v[42:43] op_sel_hi:[0,1]
	v_pk_mul_f32 v[44:45], v[160:161], v[44:45] op_sel_hi:[0,1]
	v_pk_mul_f32 v[46:47], v[160:161], v[46:47] op_sel_hi:[0,1]
	v_pk_mul_f32 v[48:49], v[160:161], v[48:49] op_sel_hi:[0,1]
	v_pk_mul_f32 v[70:71], v[162:163], v[70:71] op_sel_hi:[0,1]
	v_pk_mul_f32 v[72:73], v[162:163], v[72:73] op_sel_hi:[0,1]
	v_pk_mul_f32 v[78:79], v[162:163], v[78:79] op_sel_hi:[0,1]
	v_pk_mul_f32 v[80:81], v[162:163], v[80:81] op_sel_hi:[0,1]
	v_pk_mul_f32 v[82:83], v[162:163], v[82:83] op_sel_hi:[0,1]
	v_pk_mul_f32 v[84:85], v[162:163], v[84:85] op_sel_hi:[0,1]
	v_pk_mul_f32 v[90:91], v[162:163], v[90:91] op_sel_hi:[0,1]
	v_pk_mul_f32 v[92:93], v[162:163], v[92:93] op_sel_hi:[0,1]
	v_pk_mul_f32 v[106:107], v[164:165], v[106:107] op_sel_hi:[0,1]
	v_pk_mul_f32 v[108:109], v[164:165], v[108:109] op_sel_hi:[0,1]
	v_pk_mul_f32 v[114:115], v[164:165], v[114:115] op_sel_hi:[0,1]
	v_pk_mul_f32 v[116:117], v[164:165], v[116:117] op_sel_hi:[0,1]
	v_pk_mul_f32 v[118:119], v[164:165], v[118:119] op_sel_hi:[0,1]
	v_pk_mul_f32 v[120:121], v[164:165], v[120:121] op_sel_hi:[0,1]
	v_pk_mul_f32 v[126:127], v[164:165], v[126:127] op_sel_hi:[0,1]
	v_pk_mul_f32 v[128:129], v[164:165], v[128:129] op_sel_hi:[0,1]
	v_pk_mul_f32 v[122:123], v[166:167], v[122:123] op_sel_hi:[0,1]
	v_pk_mul_f32 v[124:125], v[166:167], v[124:125] op_sel_hi:[0,1]
	v_pk_mul_f32 v[110:111], v[166:167], v[110:111] op_sel_hi:[0,1]
	v_pk_mul_f32 v[112:113], v[166:167], v[112:113] op_sel_hi:[0,1]
	v_pk_mul_f32 v[102:103], v[166:167], v[102:103] op_sel_hi:[0,1]
	v_pk_mul_f32 v[104:105], v[166:167], v[104:105] op_sel_hi:[0,1]
	v_pk_mul_f32 v[98:99], v[166:167], v[98:99] op_sel_hi:[0,1]
	v_pk_mul_f32 v[100:101], v[166:167], v[100:101] op_sel_hi:[0,1]
	v_pk_mul_f32 v[94:95], v[168:169], v[94:95] op_sel_hi:[0,1]
	v_pk_mul_f32 v[96:97], v[168:169], v[96:97] op_sel_hi:[0,1]
	v_pk_mul_f32 v[86:87], v[168:169], v[86:87] op_sel_hi:[0,1]
	v_pk_mul_f32 v[88:89], v[168:169], v[88:89] op_sel_hi:[0,1]
	v_pk_mul_f32 v[74:75], v[168:169], v[74:75] op_sel_hi:[0,1]
	v_pk_mul_f32 v[76:77], v[168:169], v[76:77] op_sel_hi:[0,1]
	v_pk_mul_f32 v[66:67], v[168:169], v[66:67] op_sel_hi:[0,1]
	v_pk_mul_f32 v[68:69], v[168:169], v[68:69] op_sel_hi:[0,1]
	v_pk_mul_f32 v[62:63], v[170:171], v[62:63] op_sel_hi:[0,1]
	v_pk_mul_f32 v[64:65], v[170:171], v[64:65] op_sel_hi:[0,1]
	v_pk_mul_f32 v[58:59], v[170:171], v[58:59] op_sel_hi:[0,1]
	v_pk_mul_f32 v[60:61], v[170:171], v[60:61] op_sel_hi:[0,1]
	v_pk_mul_f32 v[54:55], v[170:171], v[54:55] op_sel_hi:[0,1]
	v_pk_mul_f32 v[56:57], v[170:171], v[56:57] op_sel_hi:[0,1]
	v_pk_mul_f32 v[50:51], v[170:171], v[50:51] op_sel_hi:[0,1]
	v_pk_mul_f32 v[52:53], v[170:171], v[52:53] op_sel_hi:[0,1]
	v_pk_mul_f32 v[34:35], v[172:173], v[34:35] op_sel_hi:[0,1]
	v_pk_mul_f32 v[36:37], v[172:173], v[36:37] op_sel_hi:[0,1]
	v_pk_mul_f32 v[26:27], v[172:173], v[26:27] op_sel_hi:[0,1]
	v_pk_mul_f32 v[28:29], v[172:173], v[28:29] op_sel_hi:[0,1]
	v_pk_mul_f32 v[22:23], v[172:173], v[22:23] op_sel_hi:[0,1]
	v_pk_mul_f32 v[24:25], v[172:173], v[24:25] op_sel_hi:[0,1]
	v_pk_mul_f32 v[18:19], v[172:173], v[18:19] op_sel_hi:[0,1]
	v_pk_mul_f32 v[20:21], v[172:173], v[20:21] op_sel_hi:[0,1]
	v_pk_mul_f32 v[14:15], v[174:175], v[14:15] op_sel_hi:[0,1]
	v_pk_mul_f32 v[16:17], v[174:175], v[16:17] op_sel_hi:[0,1]
	v_pk_mul_f32 v[10:11], v[174:175], v[10:11] op_sel_hi:[0,1]
	v_pk_mul_f32 v[12:13], v[174:175], v[12:13] op_sel_hi:[0,1]
	v_pk_mul_f32 v[6:7], v[174:175], v[6:7] op_sel_hi:[0,1]
	v_pk_mul_f32 v[8:9], v[174:175], v[8:9] op_sel_hi:[0,1]
	v_pk_mul_f32 v[2:3], v[174:175], v[2:3] op_sel_hi:[0,1]
	v_pk_mul_f32 v[4:5], v[174:175], v[4:5] op_sel_hi:[0,1]
	s_branch .LBB0_691
